# scan blocks: defer prefetch wait+mask to next unit top, hoist ng/D/x/z epilogue loads (ret, hg, mamba)
# speedup vs baseline: 1.0241x; 1.0241x over previous
; __device__ __forceinline__ void ret_block(ArgsP a_, unsigned char* smem) { const ArgsP a = a_;
;     ...
;     (void)s0;
;     if (nunits > 0) RT_LOAD(0);
.LBB0_229:
	v_ashrrev_i32_e32 v8, 5, v97
	v_add_u32_e32 v0, s40, v8
	v_ashrrev_i32_e32 v1, 31, v0
	v_lshlrev_b64 v[4:5], 11, v[0:1]
	v_lshlrev_b32_e32 v0, 4, v97
	s_bfe_u32 s43, s42, 0x20003
	v_and_b32_e32 v0, 0x1f0, v0
	v_lshl_or_b32 v16, s43, 9, v0
	v_or_b32_e32 v4, v4, v16
	v_lshl_add_u64 v[0:1], s[22:23], 0, v[4:5]
	v_lshl_add_u64 v[4:5], s[24:25], 0, v[4:5]
	global_load_dwordx4 v[0:3], v[0:1], off
	v_cmp_gt_i32_e32 vcc, s41, v8
	global_load_dwordx4 v[4:7], v[4:5], off
	v_add_u32_e32 v8, 0x200, v97
	v_ashrrev_i32_e32 v20, 5, v8
	v_add_u32_e32 v8, s40, v20
	v_ashrrev_i32_e32 v9, 31, v8
	v_lshlrev_b64 v[12:13], 11, v[8:9]
	v_or_b32_e32 v12, v12, v16
	v_lshl_add_u64 v[8:9], s[22:23], 0, v[12:13]
	v_lshl_add_u64 v[12:13], s[24:25], 0, v[12:13]
	global_load_dwordx4 v[8:11], v[8:9], off
	s_lshl_b32 s43, s43, 10
	global_load_dwordx4 v[12:15], v[12:13], off
	s_add_u32 s43, s75, s43
	s_addc_u32 s44, s76, 0
	s_lshl_b32 s42, s42, 7
	v_lshlrev_b32_e32 v44, 3, v19
	s_and_b32 s42, s42, 0x380
	s_add_u32 s42, s43, s42
	s_addc_u32 s43, s44, 0
	v_or_b32_e32 v38, 1, v44
	v_or_b32_e32 v42, 5, v44
	s_waitcnt vmcnt(0)
	v_cndmask_b32_e32 v3, 0, v3, vcc
	v_cndmask_b32_e32 v2, 0, v2, vcc
	v_cndmask_b32_e32 v1, 0, v1, vcc
	v_cndmask_b32_e32 v0, 0, v0, vcc
	v_cndmask_b32_e32 v7, 0, v7, vcc
	v_cndmask_b32_e32 v6, 0, v6, vcc
	v_cndmask_b32_e32 v5, 0, v5, vcc
	v_cndmask_b32_e32 v4, 0, v4, vcc
	v_cmp_gt_i32_e32 vcc, s41, v20
	v_add_u32_e32 v20, 0x400, v97
	v_ashrrev_i32_e32 v28, 5, v20
	v_add_u32_e32 v20, s40, v28
	v_ashrrev_i32_e32 v21, 31, v20
	v_lshlrev_b64 v[24:25], 11, v[20:21]
	v_or_b32_e32 v24, v24, v16
	v_lshl_add_u64 v[20:21], s[22:23], 0, v[24:25]
	v_lshl_add_u64 v[24:25], s[24:25], 0, v[24:25]
	global_load_dwordx4 v[20:23], v[20:21], off
	v_cndmask_b32_e32 v11, 0, v11, vcc
	global_load_dwordx4 v[24:27], v[24:25], off
	v_cndmask_b32_e32 v10, 0, v10, vcc
	v_cndmask_b32_e32 v9, 0, v9, vcc
	v_cndmask_b32_e32 v8, 0, v8, vcc
	v_cndmask_b32_e32 v15, 0, v15, vcc
	v_cndmask_b32_e32 v14, 0, v14, vcc
	v_cndmask_b32_e32 v13, 0, v13, vcc
	v_cndmask_b32_e32 v12, 0, v12, vcc
	v_cmp_gt_i32_e32 vcc, s41, v28
	v_add_u32_e32 v28, 0x600, v97
	v_ashrrev_i32_e32 v36, 5, v28
	v_add_u32_e32 v28, s40, v36
	v_ashrrev_i32_e32 v29, 31, v28
	v_lshlrev_b64 v[32:33], 11, v[28:29]
	v_or_b32_e32 v32, v32, v16
	v_lshlrev_b32_e32 v16, 1, v18
	v_lshl_add_u64 v[40:41], s[42:43], 0, v[16:17]
	v_lshl_add_u64 v[28:29], s[22:23], 0, v[32:33]
	v_lshl_add_u64 v[32:33], s[24:25], 0, v[32:33]
	global_load_dwordx4 v[28:31], v[28:29], off
	s_waitcnt vmcnt(2)
	v_cndmask_b32_e32 v23, 0, v23, vcc
	v_cndmask_b32_e32 v22, 0, v22, vcc
	v_cndmask_b32_e32 v21, 0, v21, vcc
	v_cndmask_b32_e32 v20, 0, v20, vcc
	s_waitcnt vmcnt(1)
	v_cndmask_b32_e32 v27, 0, v27, vcc
	v_cndmask_b32_e32 v26, 0, v26, vcc
	v_cndmask_b32_e32 v25, 0, v25, vcc
	v_cndmask_b32_e32 v24, 0, v24, vcc
	v_cmp_gt_i32_e32 vcc, s41, v36
	v_add_u32_e32 v36, s40, v44
	v_ashrrev_i32_e32 v37, 31, v36
	v_lshlrev_b64 v[36:37], 12, v[36:37]
	v_lshl_add_u64 v[36:37], v[40:41], 0, v[36:37]
	global_load_ushort v16, v[36:37], off
	v_add_u32_e32 v36, s40, v38
	v_ashrrev_i32_e32 v37, 31, v36
	v_lshlrev_b64 v[36:37], 12, v[36:37]
	global_load_dwordx4 v[32:35], v[32:33], off
	v_lshl_add_u64 v[36:37], v[40:41], 0, v[36:37]
	global_load_ushort v36, v[36:37], off
	s_waitcnt vmcnt(3)
	v_cndmask_b32_e32 v31, 0, v31, vcc
	v_cndmask_b32_e32 v30, 0, v30, vcc
	v_cndmask_b32_e32 v29, 0, v29, vcc
	v_cndmask_b32_e32 v28, 0, v28, vcc
	s_waitcnt vmcnt(1)
	v_cndmask_b32_e32 v35, 0, v35, vcc
	v_cndmask_b32_e32 v34, 0, v34, vcc
	v_cndmask_b32_e32 v33, 0, v33, vcc
	v_cndmask_b32_e32 v32, 0, v32, vcc
	v_cmp_gt_i32_e32 vcc, s41, v44
	s_waitcnt vmcnt(0)
	v_lshlrev_b32_e32 v36, 16, v36
	v_cndmask_b32_e32 v16, 0, v16, vcc
	v_cmp_gt_i32_e32 vcc, s41, v38
	s_nop 1
	v_cndmask_b32_e32 v36, 0, v36, vcc
	v_or_b32_e32 v36, v36, v16
	v_or_b32_e32 v16, 2, v44
	v_add_u32_e32 v38, s40, v16
	v_ashrrev_i32_e32 v39, 31, v38
	v_lshlrev_b64 v[38:39], 12, v[38:39]
	v_lshl_add_u64 v[38:39], v[40:41], 0, v[38:39]
	global_load_ushort v37, v[38:39], off
	v_cmp_gt_i32_e32 vcc, s41, v16
	s_waitcnt vmcnt(0)
	s_nop 0
	v_cndmask_b32_e32 v16, 0, v37, vcc
	v_or_b32_e32 v37, 3, v44
	v_add_u32_e32 v38, s40, v37
	v_ashrrev_i32_e32 v39, 31, v38
	v_lshlrev_b64 v[38:39], 12, v[38:39]
	v_lshl_add_u64 v[38:39], v[40:41], 0, v[38:39]
	v_cmp_gt_i32_e32 vcc, s41, v37
	global_load_ushort v37, v[38:39], off
	s_waitcnt vmcnt(0)
	v_lshlrev_b32_e32 v37, 16, v37
	v_cndmask_b32_e32 v37, 0, v37, vcc
	v_or_b32_e32 v37, v37, v16
	v_or_b32_e32 v16, 4, v44
	v_add_u32_e32 v38, s40, v16
	v_ashrrev_i32_e32 v39, 31, v38
	v_lshlrev_b64 v[38:39], 12, v[38:39]
	v_lshl_add_u64 v[38:39], v[40:41], 0, v[38:39]
	global_load_ushort v38, v[38:39], off
	v_cmp_gt_i32_e32 vcc, s41, v16
	s_waitcnt vmcnt(0)
	s_nop 0
	v_cndmask_b32_e32 v16, 0, v38, vcc
	v_add_u32_e32 v38, s40, v42
	v_ashrrev_i32_e32 v39, 31, v38
	v_lshlrev_b64 v[38:39], 12, v[38:39]
	v_lshl_add_u64 v[38:39], v[40:41], 0, v[38:39]
	global_load_ushort v38, v[38:39], off
	v_cmp_gt_i32_e32 vcc, s41, v42
	s_waitcnt vmcnt(0)
	v_lshlrev_b32_e32 v38, 16, v38
	v_cndmask_b32_e32 v38, 0, v38, vcc
	v_or_b32_e32 v38, v38, v16
	v_or_b32_e32 v16, 6, v44
	v_add_u32_e32 v42, s40, v16
	v_ashrrev_i32_e32 v43, 31, v42
	v_lshlrev_b64 v[42:43], 12, v[42:43]
	v_lshl_add_u64 v[42:43], v[40:41], 0, v[42:43]
	global_load_ushort v39, v[42:43], off
	v_cmp_gt_i32_e32 vcc, s41, v16
	s_waitcnt vmcnt(0)
	s_nop 0
	v_cndmask_b32_e32 v16, 0, v39, vcc
	v_or_b32_e32 v39, 7, v44
	v_add_u32_e32 v42, s40, v39
	v_ashrrev_i32_e32 v43, 31, v42
	v_lshlrev_b64 v[42:43], 12, v[42:43]
	v_lshl_add_u64 v[40:41], v[40:41], 0, v[42:43]
	v_cmp_gt_i32_e32 vcc, s41, v39
	global_load_ushort v39, v[40:41], off
	s_waitcnt vmcnt(0)
	v_lshlrev_b32_e32 v39, 16, v39
	v_cndmask_b32_e32 v39, 0, v39, vcc
	v_or_b32_e32 v39, v39, v16
	v_mov_b32_e32 v210, v20
	v_mov_b32_e32 v211, v21
	v_mov_b32_e32 v212, v22
	v_mov_b32_e32 v213, v23
	v_and_b32_e32 v202, 0xffff, v36
	v_lshrrev_b32_e32 v203, 16, v36
	v_and_b32_e32 v204, 0xffff, v37
	v_lshrrev_b32_e32 v205, 16, v37
	v_and_b32_e32 v206, 0xffff, v38
	v_lshrrev_b32_e32 v207, 16, v38
	v_and_b32_e32 v208, 0xffff, v39
	v_lshrrev_b32_e32 v209, 16, v39

; #define RT_DECODE(u, b_, h_, vs_, ck_, smp_, row0_, len_) do { if ((u) < np) { b_ = cb >> 5; h_ = (cb >> 3) & 3; vs_ = cb & 7; ck_ = (u); smp_ = false; row0_ = b_ * TP + 64 * ck_; len_ = ck_ < 32 ? 64 : 16; } \
;         else { const int it_ = (cb % 256) + ((u) - np) * G; b_ = it_ >> 5; h_ = (it_ >> 3) & 3; vs_ = it_ & 7; ck_ = 0; smp_ = true; row0_ = RP + 8 * b_; len_ = 8; } } while (0)
; __device__ __forceinline__ void ret_block(ArgsP a_, unsigned char* smem) { const ArgsP a = a_;
;     ...
;     (void)s0;
;     if (nunits > 0) RT_LOAD(0);
;     const int ntot_ = np + nsmp * REP_SMP;
;     for (int uu = 0; uu < ntot_; ++uu) { const int u = uu < np ? uu : np + (uu - np) % nsmp; const int un_ = uu + 1 < np ? uu + 1 : np + (uu + 1 - np) % nsmp;
;         int b, h, vs, ck, row0, len; bool sample; RT_DECODE(u, b, h, vs, ck, sample, row0, len);
;         const bool first = sample || ck == 0, last = sample || ck == 32;
;         const float lgam = __logf(1.f - exp2f(-5.f - (float)h));
;         if (first) state_load<256, 64>(S, AIN(3) + (((size_t)b * 4 + h) * 256) * 512 + vs * 64, 512, wid, fr, fq, !sample);
.LBB0_242:
	s_waitcnt vmcnt(0)
	v_cmp_gt_i32_e32 vcc, s89, v133
	s_nop 1
	v_cndmask_b32_e32 v3, 0, v3, vcc
	v_cndmask_b32_e32 v2, 0, v2, vcc
	v_cndmask_b32_e32 v1, 0, v1, vcc
	v_cndmask_b32_e32 v0, 0, v0, vcc
	v_cndmask_b32_e32 v7, 0, v7, vcc
	v_cndmask_b32_e32 v6, 0, v6, vcc
	v_cndmask_b32_e32 v5, 0, v5, vcc
	v_cndmask_b32_e32 v4, 0, v4, vcc
	v_cmp_gt_i32_e32 vcc, s89, v103
	s_nop 1
	v_cndmask_b32_e32 v11, 0, v11, vcc
	v_cndmask_b32_e32 v10, 0, v10, vcc
	v_cndmask_b32_e32 v9, 0, v9, vcc
	v_cndmask_b32_e32 v8, 0, v8, vcc
	v_cndmask_b32_e32 v15, 0, v15, vcc
	v_cndmask_b32_e32 v14, 0, v14, vcc
	v_cndmask_b32_e32 v13, 0, v13, vcc
	v_cndmask_b32_e32 v12, 0, v12, vcc
	v_cmp_gt_i32_e32 vcc, s89, v105
	s_nop 1
	v_cndmask_b32_e32 v23, 0, v213, vcc
	v_cndmask_b32_e32 v22, 0, v212, vcc
	v_cndmask_b32_e32 v21, 0, v211, vcc
	v_cndmask_b32_e32 v20, 0, v210, vcc
	v_cndmask_b32_e32 v27, 0, v27, vcc
	v_cndmask_b32_e32 v26, 0, v26, vcc
	v_cndmask_b32_e32 v25, 0, v25, vcc
	v_cndmask_b32_e32 v24, 0, v24, vcc
	v_cmp_gt_i32_e32 vcc, s89, v107
	s_nop 1
	v_cndmask_b32_e32 v31, 0, v31, vcc
	v_cndmask_b32_e32 v30, 0, v30, vcc
	v_cndmask_b32_e32 v29, 0, v29, vcc
	v_cndmask_b32_e32 v28, 0, v28, vcc
	v_cndmask_b32_e32 v35, 0, v35, vcc
	v_cndmask_b32_e32 v34, 0, v34, vcc
	v_cndmask_b32_e32 v33, 0, v33, vcc
	v_cndmask_b32_e32 v32, 0, v32, vcc
	v_cmp_gt_i32_e32 vcc, s89, v117
	v_lshlrev_b32_e32 v18, 16, v203
	s_nop 0
	v_cndmask_b32_e32 v16, 0, v202, vcc
	v_cmp_gt_i32_e32 vcc, s89, v109
	s_nop 1
	v_cndmask_b32_e32 v18, 0, v18, vcc
	s_nop 0
	v_or_b32_e32 v36, v18, v16
	v_cmp_gt_i32_e32 vcc, s89, v134
	v_lshlrev_b32_e32 v18, 16, v205
	s_nop 0
	v_cndmask_b32_e32 v16, 0, v204, vcc
	v_cmp_gt_i32_e32 vcc, s89, v135
	s_nop 1
	v_cndmask_b32_e32 v18, 0, v18, vcc
	s_nop 0
	v_or_b32_e32 v37, v18, v16
	v_cmp_gt_i32_e32 vcc, s89, v136
	v_lshlrev_b32_e32 v18, 16, v207
	s_nop 0
	v_cndmask_b32_e32 v16, 0, v206, vcc
	v_cmp_gt_i32_e32 vcc, s89, v137
	s_nop 1
	v_cndmask_b32_e32 v18, 0, v18, vcc
	s_nop 0
	v_or_b32_e32 v38, v18, v16
	v_cmp_gt_i32_e32 vcc, s89, v138
	v_lshlrev_b32_e32 v18, 16, v209
	s_nop 0
	v_cndmask_b32_e32 v16, 0, v208, vcc
	v_cmp_gt_i32_e32 vcc, s89, v139
	s_nop 1
	v_cndmask_b32_e32 v18, 0, v18, vcc
	s_nop 0
	v_or_b32_e32 v39, v18, v16
	s_bfe_u32 s91, s67, 0x20003
	s_and_b32 s90, s67, 7
	s_cmp_lg_u32 s87, 0
	s_cselect_b64 s[70:71], -1, 0
	s_xor_b64 s[68:69], s[34:35], -1
	s_and_b64 s[70:71], s[68:69], s[70:71]
	s_and_b64 vcc, exec, s[70:71]
	s_cbranch_vccnz .LBB0_259
	s_load_dwordx2 s[70:71], s[4:5], 0x18
	s_ashr_i32 s67, s66, 31
	s_lshl_b64 s[72:73], s[66:67], 21
	s_waitcnt lgkmcnt(0)
	s_add_u32 s67, s70, s72
	s_addc_u32 s70, s71, s73
	s_lshl_b32 s71, s91, 19
	s_add_u32 s67, s67, s71
	s_addc_u32 s70, s70, 0
	s_lshl_b32 s71, s90, 8
	s_add_u32 s72, s67, s71
	s_addc_u32 s73, s70, 0
	s_mov_b64 s[70:71], -1
	s_and_b64 vcc, exec, s[64:65]
	s_cbranch_vccz .LBB0_245
	s_mov_b64 s[70:71], 0

; __device__ __forceinline__ void ret_block(ArgsP a_, unsigned char* smem) { const ArgsP a = a_;
;     ...
;         if (uu + 1 < ntot_) RT_LOAD(un_);
.LBB0_268:
	v_add_u32_e32 v0, s67, v133
	v_ashrrev_i32_e32 v1, 31, v0
	v_add_u32_e32 v18, s67, v105
	s_bfe_u32 s65, s70, 0x20003
	v_lshlrev_b64 v[4:5], 11, v[0:1]
	v_lshlrev_b32_e32 v0, 1, v116
	v_ashrrev_i32_e32 v19, 31, v18
	v_lshl_or_b32 v16, s65, 9, v0
	v_lshlrev_b64 v[22:23], 11, v[18:19]
	v_or_b32_e32 v22, v22, v16
	v_lshl_add_u64 v[18:19], s[22:23], 0, v[22:23]
	v_lshl_add_u64 v[22:23], s[24:25], 0, v[22:23]
	s_lshl_b32 s65, s65, 10
	global_load_dwordx4 v[210:213], v[18:19], off
	s_add_u32 s65, s75, s65
	global_load_dwordx4 v[24:27], v[22:23], off
	v_add_u32_e32 v22, s67, v107
	v_ashrrev_i32_e32 v23, 31, v22
	s_addc_u32 s71, s76, 0
	s_lshl_b32 s70, s70, 7
	v_lshlrev_b64 v[22:23], 11, v[22:23]
	s_and_b32 s70, s70, 0x380
	v_or_b32_e32 v22, v22, v16
	s_add_u32 s70, s65, s70
	v_add_u32_e32 v36, s67, v117
	v_add_u32_e32 v8, s67, v103
	v_lshl_add_u64 v[28:29], s[22:23], 0, v[22:23]
	v_lshl_add_u64 v[22:23], s[24:25], 0, v[22:23]
	s_addc_u32 s71, s71, 0
	v_mov_b32_e32 v111, v17
	v_ashrrev_i32_e32 v37, 31, v36
	v_ashrrev_i32_e32 v9, 31, v8
	global_load_dwordx4 v[28:31], v[28:29], off
	v_lshlrev_b64 v[36:37], 12, v[36:37]
	global_load_dwordx4 v[32:35], v[22:23], off
	v_lshl_add_u64 v[22:23], s[70:71], 0, v[110:111]
	v_lshlrev_b64 v[12:13], 11, v[8:9]
	v_lshl_add_u64 v[36:37], v[22:23], 0, v[36:37]
	v_or_b32_e32 v4, v4, v16
	v_or_b32_e32 v12, v12, v16
	global_load_ushort v202, v[36:37], off
	v_add_u32_e32 v36, s67, v109
	v_ashrrev_i32_e32 v37, 31, v36
	v_lshlrev_b64 v[36:37], 12, v[36:37]
	v_lshl_add_u64 v[36:37], v[22:23], 0, v[36:37]
	global_load_ushort v203, v[36:37], off
	v_add_u32_e32 v36, s67, v134
	v_ashrrev_i32_e32 v37, 31, v36
	v_lshlrev_b64 v[36:37], 12, v[36:37]
	v_lshl_add_u64 v[36:37], v[22:23], 0, v[36:37]
	global_load_ushort v204, v[36:37], off
	v_add_u32_e32 v36, s67, v135
	v_ashrrev_i32_e32 v37, 31, v36
	v_lshlrev_b64 v[36:37], 12, v[36:37]
	v_lshl_add_u64 v[36:37], v[22:23], 0, v[36:37]
	global_load_ushort v205, v[36:37], off
	v_add_u32_e32 v36, s67, v136
	v_ashrrev_i32_e32 v37, 31, v36
	v_lshlrev_b64 v[36:37], 12, v[36:37]
	v_lshl_add_u64 v[36:37], v[22:23], 0, v[36:37]
	global_load_ushort v206, v[36:37], off
	v_add_u32_e32 v36, s67, v137
	v_lshl_add_u64 v[0:1], s[22:23], 0, v[4:5]
	v_lshl_add_u64 v[4:5], s[24:25], 0, v[4:5]
	v_ashrrev_i32_e32 v37, 31, v36
	global_load_dwordx4 v[0:3], v[0:1], off
	v_lshl_add_u64 v[8:9], s[22:23], 0, v[12:13]
	global_load_dwordx4 v[4:7], v[4:5], off
	v_lshl_add_u64 v[12:13], s[24:25], 0, v[12:13]
	v_lshlrev_b64 v[36:37], 12, v[36:37]
	global_load_dwordx4 v[8:11], v[8:9], off
	v_lshl_add_u64 v[36:37], v[22:23], 0, v[36:37]
	global_load_dwordx4 v[12:15], v[12:13], off
	global_load_ushort v207, v[36:37], off
	v_add_u32_e32 v36, s67, v138
	v_ashrrev_i32_e32 v37, 31, v36
	v_lshlrev_b64 v[36:37], 12, v[36:37]
	v_lshl_add_u64 v[36:37], v[22:23], 0, v[36:37]
	global_load_ushort v208, v[36:37], off
	v_add_u32_e32 v36, s67, v139
	v_ashrrev_i32_e32 v37, 31, v36
	v_lshlrev_b64 v[36:37], 12, v[36:37]
	v_lshl_add_u64 v[22:23], v[22:23], 0, v[36:37]
	global_load_ushort v209, v[22:23], off

; #define MB_DECODE(u, b_, hd_, ck_, smp_, row0_, len_) do { if ((u) < np) { b_ = cb >> 5; hd_ = cb & 31; ck_ = (u); smp_ = false; row0_ = b_ * TP + 64 * ck_; len_ = ck_ < 32 ? 64 : 16; } \
;         else { const int it_ = (cb % 256) + ((u) - np) * G; b_ = it_ >> 5; hd_ = it_ & 31; ck_ = 0; smp_ = true; row0_ = RP + 8 * b_; len_ = 8; } } while (0)
; __device__ __forceinline__ void mamba_block(ArgsP a_, unsigned char* smem) { const ArgsP a = a_;
;     ...
;     for (int uu = 0; uu < ntot_; ++uu) { const int u = uu < np ? uu : np + (uu - np) % nsmp; const int un_ = uu + 1 < np ? uu + 1 : np + (uu + 1 - np) % nsmp;
;         int b, hd, ck, row0, len; bool sample; MB_DECODE(u, b, hd, ck, sample, row0, len);
;         const bool first = sample || ck == 0, last = sample || ck == 32;
;         if (first) state_load<128, 64>(S, AIN(4) + (((size_t)b * 32 + hd) * 128) * 64, 64, wid, fr, fq, !sample);
.LBB0_333:
	s_waitcnt vmcnt(0)
	v_cmp_gt_i32_e32 vcc, s73, v85
	s_nop 1
	v_cndmask_b32_e32 v3, 0, v3, vcc
	v_cndmask_b32_e32 v2, 0, v2, vcc
	v_cndmask_b32_e32 v1, 0, v1, vcc
	v_cndmask_b32_e32 v0, 0, v0, vcc
	v_cndmask_b32_e32 v7, 0, v7, vcc
	v_cndmask_b32_e32 v6, 0, v6, vcc
	v_cndmask_b32_e32 v5, 0, v5, vcc
	v_cndmask_b32_e32 v4, 0, v4, vcc
	v_cmp_gt_i32_e32 vcc, s73, v73
	s_nop 1
	v_cndmask_b32_e32 v11, 0, v11, vcc
	v_cndmask_b32_e32 v10, 0, v10, vcc
	v_cndmask_b32_e32 v9, 0, v9, vcc
	v_cndmask_b32_e32 v8, 0, v8, vcc
	v_cndmask_b32_e32 v15, 0, v15, vcc
	v_cndmask_b32_e32 v14, 0, v14, vcc
	v_cndmask_b32_e32 v13, 0, v13, vcc
	v_cndmask_b32_e32 v12, 0, v12, vcc
	v_cmp_gt_i32_e32 vcc, s73, v78
	s_nop 1
	v_cndmask_b32_e32 v115, 0, v115, vcc
	v_cmp_gt_i32_e32 vcc, s73, v86
	s_nop 1
	v_cndmask_b32_e32 v116, 0, v116, vcc
	v_cmp_gt_i32_e32 vcc, s73, v88
	s_nop 1
	v_cndmask_b32_e32 v117, 0, v117, vcc
	v_cmp_gt_i32_e32 vcc, s73, v90
	s_nop 1
	v_cndmask_b32_e32 v120, 0, v120, vcc
	v_cmp_gt_i32_e32 vcc, s73, v92
	s_nop 1
	v_cndmask_b32_e32 v118, 0, v118, vcc
	v_cmp_gt_i32_e32 vcc, s73, v94
	s_nop 1
	v_cndmask_b32_e32 v119, 0, v119, vcc
	v_cmp_gt_i32_e32 vcc, s73, v96
	s_nop 1
	v_cndmask_b32_e32 v121, 0, v121, vcc
	v_cmp_gt_i32_e32 vcc, s73, v98
	s_nop 1
	v_cndmask_b32_e32 v122, 0, v122, vcc
	s_and_b32 s71, s64, 31
	s_cmp_lg_u32 s70, 0
	s_cselect_b64 s[76:77], -1, 0
	s_xor_b64 s[94:95], s[34:35], -1
	s_and_b64 s[76:77], s[94:95], s[76:77]
	s_and_b64 vcc, exec, s[76:77]
	s_cbranch_vccnz .LBB0_342
	s_load_dwordx2 s[76:77], s[4:5], 0x20
	s_ashr_i32 s93, s92, 31
	s_lshl_b64 s[78:79], s[92:93], 20
	s_waitcnt lgkmcnt(0)
	s_add_u32 s22, s76, s78
	s_addc_u32 s23, s77, s79
	s_lshl_b32 s64, s71, 15
	s_add_u32 s76, s22, s64
	s_addc_u32 s77, s23, 0
	s_mov_b64 s[78:79], -1
	s_and_b64 vcc, exec, s[74:75]
	s_cbranch_vccz .LBB0_336
	s_mov_b64 s[78:79], 0

; __device__ __forceinline__ unsigned cvt_pk_bf16(float lo, float hi) { unsigned r; asm("v_cvt_pk_bf16_f32 %0, %1, %2" : "=v"(r) : "v"(lo), "v"(hi)); return r; }
; template <int DK, int DV, bool SEPQ> ...
;     ...
;         for (int vt = 0; vt < NVT; ++vt) { const f32x4 s = S[ct][vt]; u32x2 w; w.x = cvt_pk_bf16(s[0], s[1]); w.y = cvt_pk_bf16(s[2], s[3]);
;             *(u32x2*)(ST + (16 * vt + fr) * LQ + 16 * (wid * NCTW + ct) + 4 * fq) = w; }
;     __syncthreads();
;     {
;         const float gi_i = GI[16 * m + fr];
;         const int n0 = 2 * hw, n1 = 2 * hw + 1; const bool do0 = n0 <= m, do1 = n1 <= m;
;         f32x4 acc0 = {0.f, 0.f, 0.f, 0.f}, acc1 = {0.f, 0.f, 0.f, 0.f};
; #pragma unroll
;         for (int vt = 0; vt < NVTW; ++vt) O[vt] = (f32x4){0.f, 0.f, 0.f, 0.f};
; #pragma unroll
;         for (int ks = 0; ks < DK / 32; ++ks) {
;             const bf16x8 qf = *(const bf16x8*)(QA + (16 * m + fr) * LQ + 32 * ks + 8 * fq);
;             if (do0) { const bf16x8 kf = *(const bf16x8*)(KB + (16 * n0 + fr) * LQ + 32 * ks + 8 * fq); acc0 = __builtin_amdgcn_mfma_f32_16x16x32_bf16(kf, qf, acc0, 0, 0, 0); }
; __device__ __forceinline__ void mamba_block(ArgsP a_, unsigned char* smem) { const ArgsP a = a_;
;     ...
;         if (i < len) { const float Dh = AIN(24)[hd];
; #pragma unroll
;             for (int vt = 0; vt < 2; ++vt) { const int v = 16 * (hw * 2 + vt) + 4 * fq; const size_t o = (size_t)(row0 + i) * 2048 + hd * 64 + v;
;                 const u32x2 xt = *(const u32x2*)(XC + (size_t)(row0 + i) * 4096 + hd * 64 + v); const u32x2 zt = *(const u32x2*)(ZG + o);
.LBB0_353:
	s_lshl_b32 s22, s76, 6
	v_add_u32_e32 v0, s93, v85
	s_and_b32 s74, s22, 0x700
	s_mov_b32 s75, s12
	v_ashrrev_i32_e32 v1, 31, v0
	v_lshl_add_u64 v[8:9], v[60:61], 0, s[74:75]
	v_lshlrev_b64 v[0:1], 13, v[0:1]
	v_add_u32_e32 v10, s93, v73
	v_lshl_add_u64 v[0:1], v[8:9], 0, v[0:1]
	v_ashrrev_i32_e32 v11, 31, v10
	s_and_b32 s64, s76, 31
	v_add_co_u32_e32 v4, vcc, 0x1000, v0
	v_lshlrev_b64 v[10:11], 13, v[10:11]
	v_add_u32_e32 v18, s93, v78
	v_addc_co_u32_e32 v5, vcc, 0, v1, vcc
	v_lshl_add_u64 v[8:9], v[8:9], 0, v[10:11]
	s_lshl_b32 s76, s64, 7
	s_mov_b32 s77, s12
	v_ashrrev_i32_e32 v19, 31, v18
	v_add_co_u32_e32 v12, vcc, 0x1000, v8
	v_lshl_add_u64 v[40:41], v[62:63], 0, s[76:77]
	v_lshlrev_b64 v[18:19], 13, v[18:19]
	v_addc_co_u32_e32 v13, vcc, 0, v9, vcc
	v_lshl_add_u64 v[18:19], v[40:41], 0, v[18:19]
	global_load_dwordx4 v[0:3], v[4:5], off
	s_nop 0
	global_load_dwordx4 v[4:7], v[4:5], off offset:2048
	s_nop 0
	global_load_dwordx4 v[8:11], v[12:13], off
	s_nop 0
	global_load_dwordx4 v[12:15], v[12:13], off offset:2048
	v_add_u32_e32 v36, s93, v88
	global_load_ushort v115, v[18:19], off
	v_add_u32_e32 v18, s93, v86
	v_ashrrev_i32_e32 v19, 31, v18
	v_ashrrev_i32_e32 v37, 31, v36
	v_lshlrev_b64 v[18:19], 13, v[18:19]
	v_lshlrev_b64 v[36:37], 13, v[36:37]
	v_lshl_add_u64 v[18:19], v[40:41], 0, v[18:19]
	v_lshl_add_u64 v[36:37], v[40:41], 0, v[36:37]
	global_load_ushort v116, v[18:19], off
	v_add_u32_e32 v38, s93, v92
	global_load_ushort v117, v[36:37], off
	v_add_u32_e32 v36, s93, v90
	v_ashrrev_i32_e32 v37, 31, v36
	v_ashrrev_i32_e32 v39, 31, v38
	v_lshlrev_b64 v[36:37], 13, v[36:37]
	v_lshlrev_b64 v[38:39], 13, v[38:39]
	v_lshl_add_u64 v[36:37], v[40:41], 0, v[36:37]
	v_lshl_add_u64 v[38:39], v[40:41], 0, v[38:39]
	global_load_ushort v120, v[36:37], off
	v_add_u32_e32 v42, s93, v96
	global_load_ushort v118, v[38:39], off
	v_add_u32_e32 v38, s93, v94
	v_ashrrev_i32_e32 v39, 31, v38
	v_ashrrev_i32_e32 v43, 31, v42
	v_lshlrev_b64 v[38:39], 13, v[38:39]
	v_lshlrev_b64 v[42:43], 13, v[42:43]
	v_lshl_add_u64 v[38:39], v[40:41], 0, v[38:39]
	v_lshl_add_u64 v[42:43], v[40:41], 0, v[42:43]
	global_load_ushort v119, v[38:39], off
	global_load_ushort v121, v[42:43], off
	v_add_u32_e32 v42, s93, v98
	v_ashrrev_i32_e32 v43, 31, v42
	v_lshlrev_b64 v[42:43], 13, v[42:43]
	v_lshl_add_u64 v[40:41], v[40:41], 0, v[42:43]
	global_load_ushort v122, v[40:41], off
	s_and_saveexec_b64 s[96:97], s[40:41]
	s_cbranch_execz .LBB0_355
	v_add_u32_e32 v42, s93, v57
	v_ashrrev_i32_e32 v43, 31, v42
	v_readlane_b32 s22, v255, 28
	v_lshlrev_b64 v[42:43], 10, v[42:43]
	v_readlane_b32 s23, v255, 29
	s_nop 1
	v_lshl_add_u64 v[42:43], s[22:23], 0, v[42:43]
	s_lshl_b32 s22, s64, 2
	s_mov_b32 s23, s12
	v_lshl_add_u64 v[42:43], v[42:43], 0, s[22:23]
	global_load_dword v67, v[42:43], off
.LBB0_355:
	s_or_b64 exec, exec, s[96:97]
	v_readlane_b32 s93, v254, 53
.LBB0_356:
	s_load_dwordx2 s[22:23], s[4:5], 0xc0
	v_add_u32_e32 v212, s72, v71
	v_ashrrev_i32_e32 v213, 31, v212
	v_lshlrev_b64 v[214:215], 11, v[212:213]
	v_lshlrev_b64 v[212:213], 13, v[212:213]
	v_readlane_b32 s74, v255, 12
	v_readlane_b32 s75, v255, 13
	v_lshl_or_b32 v216, s71, 6, v214
	v_or_b32_e32 v214, v216, v66
	s_nop 0
	v_lshl_add_u64 v[212:213], s[74:75], 0, v[212:213]
	s_lshl_b32 s74, s71, 7
	s_mov_b32 s75, s12
	v_lshl_add_u64 v[212:213], v[212:213], 0, s[74:75]
	v_lshlrev_b32_e32 v218, 1, v66
	v_mov_b32_e32 v219, 0
	v_lshl_add_u64 v[212:213], v[212:213], 0, v[218:219]
	v_lshlrev_b64 v[218:219], 1, v[214:215]
	global_load_dwordx2 v[202:203], v[212:213], off
	v_lshl_add_u64 v[218:219], s[24:25], 0, v[218:219]
	global_load_dwordx2 v[204:205], v[218:219], off
	global_load_dwordx2 v[206:207], v[212:213], off offset:32
	v_or_b32_e32 v214, v216, v68
	v_lshlrev_b64 v[218:219], 1, v[214:215]
	v_lshl_add_u64 v[218:219], s[24:25], 0, v[218:219]
	global_load_dwordx2 v[208:209], v[218:219], off
	s_lshl_b32 s74, s71, 2
	v_mov_b32_e32 v217, s74
	s_waitcnt lgkmcnt(0)
	global_load_dword v210, v217, s[22:23]
	v_cvt_pk_bf16_f32 v18, v20, v21
	v_cvt_pk_bf16_f32 v19, v22, v23
	ds_write_b64 v109, v[18:19]
	v_cvt_pk_bf16_f32 v18, v24, v25
	v_cvt_pk_bf16_f32 v19, v26, v27
	ds_write_b64 v109, v[18:19] offset:4352
	v_cvt_pk_bf16_f32 v18, v28, v29
	v_cvt_pk_bf16_f32 v19, v30, v31
	ds_write_b64 v109, v[18:19] offset:8704
	v_cvt_pk_bf16_f32 v18, v32, v33
	v_cvt_pk_bf16_f32 v19, v34, v35
	ds_write_b64 v109, v[18:19] offset:13056
	s_waitcnt lgkmcnt(0)
	s_barrier
	ds_read_b32 v123, v81
	ds_read_b128 v[48:51], v64
	v_mov_b32_e32 v18, v17
	v_mov_b32_e32 v19, v17
	v_mov_b32_e32 v16, v17
	v_mov_b64_e32 v[42:43], v[18:19]
	v_mov_b64_e32 v[40:41], v[16:17]
	s_and_saveexec_b64 s[74:75], s[42:43]
	s_cbranch_execz .LBB0_358
	ds_read_b128 v[36:39], v65 offset:17408
	s_waitcnt lgkmcnt(0)
	v_mfma_f32_16x16x32_bf16 v[40:43], v[36:39], v[48:51], 0

; template <int DK, int DV, bool SEPQ> ...
;     ...
;         for (int nn = 0; nn < 2; ++nn) {
;             const int n = 2 * hw + nn; const f32x4 acc = nn == 0 ? acc0 : acc1;
;             const f32x4 gj = *(const f32x4*)(GI + 16 * n + 4 * fq); const int i = 16 * m + fr, j0 = 16 * n + 4 * fq; float p[4];
; #pragma unroll
;             for (int e = 0; e < 4; ++e) p[e] = (j0 + e <= i) ? acc[e] * __expf(gi_i - gj[e]) : 0.f;
;             u32x2 w; w.x = cvt_pk_bf16(p[0], p[1]); w.y = cvt_pk_bf16(p[2], p[3]); *(u32x2*)(P + (16 * m + fr) * LJ + j0) = w;
;         }
;         const float ei = __expf(gi_i);
; #pragma unroll
;         for (int vt = 0; vt < NVTW; ++vt) O[vt] = O[vt] * ei;
;     }
;     __syncthreads();
; #pragma unroll
;     for (int ks = 0; ks < 2; ++ks) { const bf16x8 pf = *(const bf16x8*)(P + (16 * m + fr) * LJ + 32 * ks + 8 * fq);
; #pragma unroll
;         for (int vt = 0; vt < NVTW; ++vt) { const bf16x8 vf = *(const bf16x8*)(VT + (16 * (hw * NVTW + vt) + fr) * LJ + 32 * ks + 8 * fq); O[vt] = __builtin_amdgcn_mfma_f32_16x16x32_bf16(vf, pf, O[vt], 0, 0, 0); } }
; #pragma unroll
;     for (int ct = 0; ct < NCTW; ++ct) { const int ctg = wid * NCTW + ct; const f32x4 dec = *(const f32x4*)(SDEC + 16 * ctg + 4 * fq);
; #pragma unroll
;         for (int vt = 0; vt < NVT; ++vt) S[ct][vt] = S[ct][vt] * dec;
; #pragma unroll
;         for (int ks = 0; ks < 2; ++ks) { const bf16x8 kf = *(const bf16x8*)(KT + (16 * ctg + fr) * LJ + 32 * ks + 8 * fq);
; #pragma unroll
;             for (int vt = 0; vt < NVT; ++vt) { const bf16x8 vf = *(const bf16x8*)(VT2 + (16 * vt + fr) * LJ + 32 * ks + 8 * fq); S[ct][vt] = __builtin_amdgcn_mfma_f32_16x16x32_bf16(kf, vf, S[ct][vt], 0, 0, 0); } } }
; __device__ __forceinline__ void mamba_block(ArgsP a_, unsigned char* smem) { const ArgsP a = a_;
;     ...
;         const int m = wid >> 1, hw = wid & 1, i = 16 * m + fr;
;         if (i < len) { const float Dh = AIN(24)[hd];
; #pragma unroll
;             for (int vt = 0; vt < 2; ++vt) { const int v = 16 * (hw * 2 + vt) + 4 * fq; const size_t o = (size_t)(row0 + i) * 2048 + hd * 64 + v;
;                 const u32x2 xt = *(const u32x2*)(XC + (size_t)(row0 + i) * 4096 + hd * 64 + v); const u32x2 zt = *(const u32x2*)(ZG + o);
;                 const f32x4 xs = {__uint_as_float(xt.x << 16), __uint_as_float(xt.x & 0xffff0000u), __uint_as_float(xt.y << 16), __uint_as_float(xt.y & 0xffff0000u)};
.LBB0_372:
	s_or_b64 exec, exec, s[74:75]
	ds_read_b128 v[124:127], v114 offset:192
	v_cmp_gt_i32_e32 vcc, s73, v71
	s_waitcnt lgkmcnt(0)
	v_mfma_f32_16x16x32_bf16 v[44:47], v[124:127], v[52:55], v[44:47]
	ds_read_b128 v[124:127], v114 offset:4544
	s_waitcnt lgkmcnt(0)
	v_mfma_f32_16x16x32_bf16 v[48:51], v[124:127], v[52:55], v[48:51]
	ds_read_b128 v[52:55], v82
	s_waitcnt lgkmcnt(0)
	v_sub_f32_e32 v16, v123, v52
	v_mul_f32_e32 v16, 0x3fb8aa3b, v16
	v_exp_f32_e32 v16, v16
	v_sub_f32_e32 v18, v123, v53
	v_sub_f32_e32 v19, v123, v54
	v_mul_f32_e32 v18, 0x3fb8aa3b, v18
	v_mul_f32_e32 v16, v40, v16
	v_mul_f32_e32 v19, 0x3fb8aa3b, v19
	v_sub_f32_e32 v40, v123, v55
	v_exp_f32_e32 v18, v18
	v_exp_f32_e32 v19, v19
	v_mul_f32_e32 v40, 0x3fb8aa3b, v40
	v_exp_f32_e32 v40, v40
	v_mul_f32_e32 v18, v41, v18
	v_mul_f32_e32 v19, v42, v19
	v_cndmask_b32_e64 v18, 0, v18, s[48:49]
	v_cndmask_b32_e64 v19, v19, 0, s[50:51]
	v_mul_f32_e32 v40, v43, v40
	v_cndmask_b32_e64 v16, v16, 0, s[46:47]
	v_cndmask_b32_e64 v40, v40, 0, s[52:53]
	v_cvt_pk_bf16_f32 v18, v16, v18
	v_cvt_pk_bf16_f32 v19, v19, v40
	ds_write_b64 v83, v[18:19]
	ds_read_b128 v[40:43], v82 offset:64
	s_waitcnt lgkmcnt(0)
	v_sub_f32_e32 v16, v123, v40
	v_mul_f32_e32 v16, 0x3fb8aa3b, v16
	v_sub_f32_e32 v18, v123, v41
	v_exp_f32_e32 v16, v16
	v_mul_f32_e32 v18, 0x3fb8aa3b, v18
	v_exp_f32_e32 v18, v18
	v_sub_f32_e32 v19, v123, v42
	v_mul_f32_e32 v16, v36, v16
	v_sub_f32_e32 v36, v123, v43
	v_mul_f32_e32 v18, v37, v18
	v_mul_f32_e32 v19, 0x3fb8aa3b, v19
	v_mul_f32_e32 v36, 0x3fb8aa3b, v36
	v_cndmask_b32_e64 v16, v16, 0, s[54:55]
	v_cndmask_b32_e64 v18, 0, v18, s[56:57]
	v_exp_f32_e32 v19, v19
	v_exp_f32_e32 v36, v36
	v_cvt_pk_bf16_f32 v18, v16, v18
	v_mul_f32_e32 v16, 0x3fb8aa3b, v123
	v_exp_f32_e32 v16, v16
	v_mul_f32_e32 v19, v38, v19
	v_mul_f32_e32 v36, v39, v36
	v_cndmask_b32_e64 v19, v19, 0, s[58:59]
	v_cndmask_b32_e64 v36, v36, 0, s[60:61]
	v_cvt_pk_bf16_f32 v19, v19, v36
	ds_write_b64 v83, v[18:19] offset:32
	v_pk_mul_f32 v[36:37], v[16:17], v[44:45] op_sel_hi:[0,1]
	v_pk_mul_f32 v[38:39], v[16:17], v[46:47] op_sel_hi:[0,1]
	v_pk_mul_f32 v[40:41], v[16:17], v[48:49] op_sel_hi:[0,1]
	v_pk_mul_f32 v[42:43], v[16:17], v[50:51] op_sel_hi:[0,1]
	s_waitcnt lgkmcnt(0)
	s_barrier
	ds_read_b128 v[44:47], v84
	ds_read_b128 v[48:51], v110 offset:53248
	s_waitcnt lgkmcnt(0)
	v_mfma_f32_16x16x32_bf16 v[36:39], v[48:51], v[44:47], v[36:39]
	ds_read_b128 v[48:51], v110 offset:55552
	s_waitcnt lgkmcnt(0)
	v_mfma_f32_16x16x32_bf16 v[44:47], v[48:51], v[44:47], v[40:43]
	ds_read_b128 v[48:51], v84 offset:64
	s_nop 1
	ds_read_b128 v[40:43], v110 offset:53312
	s_waitcnt lgkmcnt(0)
	v_mfma_f32_16x16x32_bf16 v[40:43], v[40:43], v[48:51], v[36:39]
	s_nop 2
	ds_read_b128 v[36:39], v110 offset:55616
	s_waitcnt lgkmcnt(0)
	v_mfma_f32_16x16x32_bf16 v[36:39], v[36:39], v[48:51], v[44:47]
	s_nop 2
	ds_read_b128 v[44:47], v111
	s_waitcnt lgkmcnt(0)
	v_pk_mul_f32 v[22:23], v[22:23], v[46:47]
	v_pk_mul_f32 v[20:21], v[20:21], v[44:45]
	v_pk_mul_f32 v[24:25], v[24:25], v[44:45]
	v_pk_mul_f32 v[26:27], v[26:27], v[46:47]
	v_pk_mul_f32 v[28:29], v[28:29], v[44:45]
	v_pk_mul_f32 v[30:31], v[30:31], v[46:47]
	v_pk_mul_f32 v[32:33], v[32:33], v[44:45]
	v_pk_mul_f32 v[34:35], v[34:35], v[46:47]
	ds_read_b128 v[44:47], v70 offset:34816
	ds_read_b128 v[48:51], v112 offset:62464
	s_waitcnt lgkmcnt(0)
	v_mfma_f32_16x16x32_bf16 v[18:21], v[44:47], v[48:51], v[20:23]
	ds_read_b128 v[48:51], v112 offset:64768
	s_waitcnt lgkmcnt(0)
	v_mfma_f32_16x16x32_bf16 v[24:27], v[44:47], v[48:51], v[24:27]
	ds_read_b128 v[48:51], v113 offset:62464
	s_waitcnt lgkmcnt(0)
	v_mfma_f32_16x16x32_bf16 v[28:31], v[44:47], v[48:51], v[28:31]
	ds_read_b128 v[48:51], v113 offset:64768
	s_waitcnt lgkmcnt(0)
	v_mfma_f32_16x16x32_bf16 v[32:35], v[44:47], v[48:51], v[32:35]
	ds_read_b128 v[44:47], v70 offset:34880
	ds_read_b128 v[48:51], v112 offset:62528
	s_waitcnt lgkmcnt(0)
	v_mfma_f32_16x16x32_bf16 v[20:23], v[44:47], v[48:51], v[18:21]
	ds_read_b128 v[48:51], v112 offset:64832
	s_waitcnt lgkmcnt(0)
	v_mfma_f32_16x16x32_bf16 v[24:27], v[44:47], v[48:51], v[24:27]
	ds_read_b128 v[48:51], v113 offset:62528
	s_waitcnt lgkmcnt(0)
	v_mfma_f32_16x16x32_bf16 v[28:31], v[44:47], v[48:51], v[28:31]
	ds_read_b128 v[48:51], v113 offset:64832
	s_waitcnt lgkmcnt(0)
	v_mfma_f32_16x16x32_bf16 v[32:35], v[44:47], v[48:51], v[32:35]
	s_and_saveexec_b64 s[74:75], vcc
	s_cbranch_execz .LBB0_374
	v_add_u32_e32 v44, s72, v71
	v_ashrrev_i32_e32 v45, 31, v44
	s_waitcnt vmcnt(0)
	v_mov_b32_e32 v18, v210
	v_readlane_b32 s22, v255, 12
	v_lshlrev_b64 v[46:47], 11, v[44:45]
	v_lshlrev_b64 v[44:45], 13, v[44:45]
	v_readlane_b32 s23, v255, 13
	v_lshl_or_b32 v19, s71, 6, v46
	v_or_b32_e32 v46, v19, v66
	v_lshl_add_u64 v[44:45], s[22:23], 0, v[44:45]
	s_lshl_b32 s22, s71, 7
	s_mov_b32 s23, s12
	v_lshl_add_u64 v[44:45], v[44:45], 0, s[22:23]
	v_lshlrev_b32_e32 v16, 1, v66
	v_lshl_add_u64 v[44:45], v[44:45], 0, v[16:17]
	v_lshlrev_b64 v[50:51], 1, v[46:47]
	v_mov_b32_e32 v48, v202
	v_mov_b32_e32 v49, v203
	v_lshl_add_u64 v[52:53], s[24:25], 0, v[50:51]
	v_mov_b32_e32 v52, v204
	v_mov_b32_e32 v53, v205
	v_or_b32_e32 v46, v19, v68
	v_lshlrev_b32_e32 v54, 16, v48
	v_and_b32_e32 v55, 0xffff0000, v48
	v_lshlrev_b32_e32 v48, 16, v49
	v_and_b32_e32 v49, 0xffff0000, v49
	v_lshlrev_b32_e32 v124, 16, v52
	v_and_b32_e32 v125, 0xffff0000, v52
	v_lshlrev_b32_e32 v52, 16, v53
	v_and_b32_e32 v53, 0xffff0000, v53
	v_pk_fma_f32 v[40:41], v[18:19], v[54:55], v[40:41] op_sel_hi:[0,1,1]
	v_pk_fma_f32 v[42:43], v[18:19], v[48:49], v[42:43] op_sel_hi:[0,1,1]
	v_pk_mul_f32 v[42:43], v[42:43], v[52:53]
	v_pk_mul_f32 v[40:41], v[40:41], v[124:125]
	s_nop 0
	v_cvt_pk_bf16_f32 v40, v40, v41
	v_cvt_pk_bf16_f32 v41, v42, v43
	v_lshl_add_u64 v[42:43], s[26:27], 0, v[50:51]
	global_store_dwordx2 v[42:43], v[40:41], off
	v_lshlrev_b64 v[42:43], 1, v[46:47]
	v_mov_b32_e32 v40, v206
	v_mov_b32_e32 v41, v207
	v_lshl_add_u64 v[44:45], s[24:25], 0, v[42:43]
	v_mov_b32_e32 v44, v208
	v_mov_b32_e32 v45, v209
	v_lshlrev_b32_e32 v46, 16, v40
	v_and_b32_e32 v47, 0xffff0000, v40
	v_lshlrev_b32_e32 v40, 16, v41
	v_and_b32_e32 v41, 0xffff0000, v41
	v_lshlrev_b32_e32 v48, 16, v44
	v_and_b32_e32 v49, 0xffff0000, v44
	v_lshlrev_b32_e32 v44, 16, v45
	v_and_b32_e32 v45, 0xffff0000, v45
	v_pk_fma_f32 v[36:37], v[18:19], v[46:47], v[36:37] op_sel_hi:[0,1,1]
	v_pk_fma_f32 v[18:19], v[18:19], v[40:41], v[38:39] op_sel_hi:[0,1,1]
	v_pk_mul_f32 v[18:19], v[18:19], v[44:45]
	v_pk_mul_f32 v[36:37], v[36:37], v[48:49]
	s_nop 0
	v_cvt_pk_bf16_f32 v36, v36, v37
	v_cvt_pk_bf16_f32 v37, v18, v19
	v_lshl_add_u64 v[18:19], s[26:27], 0, v[42:43]
	global_store_dwordx2 v[18:19], v[36:37], off

; __device__ __forceinline__ void hg_block(ArgsP a_, int jl, unsigned char* smem) { const ArgsP a = a_;
;     ...
;         { f32x4 run = {0.f, 0.f, 0.f, 0.f};
; #pragma unroll
;           for (int r = 0; r < 4; ++r) { run = run + lf4[r]; cs[r] = run; }
;           *(f32x4*)(TOT + rg * 128 + c4) = run; }
;         __syncthreads();
;         { f32x4 pre = {0.f, 0.f, 0.f, 0.f}, gmid = pre, glast = pre;
; #pragma unroll
;           for (int k = 0; k < 16; ++k) { const f32x4 t = *(const f32x4*)(TOT + k * 128 + c4); if (k < rg) pre = pre + t; if (k < 8) gmid = gmid + t; glast = glast + t; }
;           f32x4 Emid, Elm;
; #pragma unroll
;           for (int e = 0; e < 4; ++e) { Emid[e] = __expf(gmid[e]); Elm[e] = __expf(glast[e] - gmid[e]); }
.LBB0_412:
	s_waitcnt vmcnt(0)
	v_cmp_gt_i32_e32 vcc, s64, v136
	s_nop 1
	v_cndmask_b32_e32 v0, 0, v0, vcc
	v_cndmask_b32_e32 v1, 0, v1, vcc
	v_cndmask_b32_e32 v2, 0, v2, vcc
	v_cndmask_b32_e32 v3, 0, v3, vcc
	v_cndmask_b32_e32 v82, 0, v82, vcc
	v_cndmask_b32_e32 v83, 0, v83, vcc
	v_cndmask_b32_e32 v78, 0, v78, vcc
	v_cndmask_b32_e32 v79, 0, v79, vcc
	v_cndmask_b32_e32 v80, 0, v80, vcc
	v_cndmask_b32_e32 v81, 0, v81, vcc
	v_cmp_gt_i32_e32 vcc, s64, v107
	s_nop 1
	v_cndmask_b32_e32 v4, 0, v4, vcc
	v_cndmask_b32_e32 v5, 0, v5, vcc
	v_cndmask_b32_e32 v6, 0, v6, vcc
	v_cndmask_b32_e32 v7, 0, v7, vcc
	v_cndmask_b32_e32 v90, 0, v90, vcc
	v_cndmask_b32_e32 v91, 0, v91, vcc
	v_cndmask_b32_e32 v86, 0, v86, vcc
	v_cndmask_b32_e32 v87, 0, v87, vcc
	v_cndmask_b32_e32 v88, 0, v88, vcc
	v_cndmask_b32_e32 v89, 0, v89, vcc
	v_cmp_gt_i32_e32 vcc, s64, v109
	s_nop 1
	v_cndmask_b32_e32 v8, 0, v8, vcc
	v_cndmask_b32_e32 v9, 0, v9, vcc
	v_cndmask_b32_e32 v10, 0, v10, vcc
	v_cndmask_b32_e32 v11, 0, v11, vcc
	v_cndmask_b32_e32 v102, 0, v102, vcc
	v_cndmask_b32_e32 v103, 0, v103, vcc
	v_cndmask_b32_e32 v98, 0, v98, vcc
	v_cndmask_b32_e32 v99, 0, v99, vcc
	v_cndmask_b32_e32 v100, 0, v100, vcc
	v_cndmask_b32_e32 v101, 0, v101, vcc
	v_cmp_gt_i32_e32 vcc, s64, v164
	s_nop 1
	v_cndmask_b32_e32 v12, 0, v12, vcc
	v_cndmask_b32_e32 v13, 0, v13, vcc
	v_cndmask_b32_e32 v14, 0, v14, vcc
	v_cndmask_b32_e32 v15, 0, v15, vcc
	v_cndmask_b32_e32 v120, 0, v120, vcc
	v_cndmask_b32_e32 v121, 0, v121, vcc
	v_cndmask_b32_e32 v110, 0, v110, vcc
	v_cndmask_b32_e32 v111, 0, v111, vcc
	v_cndmask_b32_e32 v112, 0, v112, vcc
	v_cndmask_b32_e32 v113, 0, v113, vcc
	v_pk_add_f32 v[62:63], v[2:3], 0 op_sel_hi:[1,0]
	v_pk_add_f32 v[64:65], v[0:1], 0 op_sel_hi:[1,0]
	v_pk_add_f32 v[58:59], v[62:63], v[6:7]
	v_pk_add_f32 v[60:61], v[64:65], v[4:5]
	v_pk_add_f32 v[54:55], v[58:59], v[10:11]
	v_pk_add_f32 v[56:57], v[60:61], v[8:9]
	v_pk_add_f32 v[52:53], v[54:55], v[14:15]
	v_pk_add_f32 v[50:51], v[56:57], v[12:13]
	ds_write_b128 v168, v[50:53]
	s_waitcnt vmcnt(0) lgkmcnt(0)
	s_barrier
	ds_read_b128 v[66:69], v135
	v_lshlrev_b32_e32 v175, 16, v78
	v_and_b32_e32 v178, 0xffff0000, v79
	s_mov_b32 s49, 0xffff0000
	s_waitcnt lgkmcnt(0)
	v_pk_add_f32 v[70:71], v[68:69], 0 op_sel_hi:[1,0]
	v_pk_add_f32 v[72:73], v[66:67], 0 op_sel_hi:[1,0]
	ds_read_b128 v[66:69], v135 offset:512
	v_cndmask_b32_e64 v75, 0, v73, s[66:67]
	v_cndmask_b32_e64 v74, 0, v72, s[66:67]
	v_cndmask_b32_e64 v77, 0, v71, s[66:67]
	v_cndmask_b32_e64 v76, 0, v70, s[66:67]
	s_waitcnt lgkmcnt(0)
	v_pk_add_f32 v[126:127], v[66:67], v[74:75]
	v_pk_add_f32 v[128:129], v[68:69], v[76:77]
	v_pk_add_f32 v[70:71], v[70:71], v[68:69]
	v_pk_add_f32 v[72:73], v[72:73], v[66:67]
	ds_read_b128 v[66:69], v135 offset:1024
	v_cndmask_b32_e64 v75, v75, v127, s[68:69]
	v_cndmask_b32_e64 v74, v74, v126, s[68:69]
	v_cndmask_b32_e64 v77, v77, v129, s[68:69]
	v_cndmask_b32_e64 v76, v76, v128, s[68:69]
	s_waitcnt lgkmcnt(0)
	v_pk_add_f32 v[126:127], v[66:67], v[74:75]
	v_pk_add_f32 v[128:129], v[68:69], v[76:77]
	v_pk_add_f32 v[70:71], v[70:71], v[68:69]
	v_pk_add_f32 v[72:73], v[72:73], v[66:67]
	ds_read_b128 v[66:69], v135 offset:1536
	v_cndmask_b32_e64 v75, v75, v127, s[70:71]
	v_cndmask_b32_e64 v74, v74, v126, s[70:71]
	v_cndmask_b32_e64 v77, v77, v129, s[70:71]
	v_cndmask_b32_e64 v76, v76, v128, s[70:71]
	s_waitcnt lgkmcnt(0)
	v_pk_add_f32 v[126:127], v[66:67], v[74:75]
	v_pk_add_f32 v[128:129], v[68:69], v[76:77]
	v_pk_add_f32 v[70:71], v[70:71], v[68:69]
	v_pk_add_f32 v[72:73], v[72:73], v[66:67]
	ds_read_b128 v[66:69], v135 offset:2048
	v_cndmask_b32_e64 v75, v75, v127, s[72:73]
	v_cndmask_b32_e64 v74, v74, v126, s[72:73]
	v_cndmask_b32_e64 v77, v77, v129, s[72:73]
	v_cndmask_b32_e64 v76, v76, v128, s[72:73]
	s_waitcnt lgkmcnt(0)
	v_pk_add_f32 v[126:127], v[66:67], v[74:75]
	v_pk_add_f32 v[128:129], v[68:69], v[76:77]
	v_pk_add_f32 v[70:71], v[70:71], v[68:69]
	v_pk_add_f32 v[72:73], v[72:73], v[66:67]
	ds_read_b128 v[66:69], v135 offset:2560
	v_cndmask_b32_e64 v75, v75, v127, s[74:75]
	v_cndmask_b32_e64 v74, v74, v126, s[74:75]
	v_cndmask_b32_e64 v77, v77, v129, s[74:75]
	v_cndmask_b32_e64 v76, v76, v128, s[74:75]
	s_waitcnt lgkmcnt(0)
	v_pk_add_f32 v[126:127], v[66:67], v[74:75]
	v_pk_add_f32 v[128:129], v[68:69], v[76:77]
	v_pk_add_f32 v[70:71], v[70:71], v[68:69]
	v_pk_add_f32 v[72:73], v[72:73], v[66:67]
	ds_read_b128 v[66:69], v135 offset:3072
	v_cndmask_b32_e64 v75, v75, v127, s[76:77]
	v_cndmask_b32_e64 v74, v74, v126, s[76:77]
	v_cndmask_b32_e64 v77, v77, v129, s[76:77]
	v_cndmask_b32_e64 v76, v76, v128, s[76:77]
	s_waitcnt lgkmcnt(0)
	v_pk_add_f32 v[126:127], v[66:67], v[74:75]
	v_pk_add_f32 v[128:129], v[68:69], v[76:77]
	v_cndmask_b32_e64 v75, v75, v127, s[78:79]
	v_cndmask_b32_e64 v74, v74, v126, s[78:79]
	v_pk_add_f32 v[126:127], v[70:71], v[68:69]
	ds_read_b128 v[68:71], v135 offset:3584
	v_cndmask_b32_e64 v77, v77, v129, s[78:79]
	v_cndmask_b32_e64 v76, v76, v128, s[78:79]
	v_pk_add_f32 v[72:73], v[72:73], v[66:67]
	s_waitcnt lgkmcnt(0)
	v_pk_add_f32 v[66:67], v[68:69], v[74:75]
	v_pk_add_f32 v[128:129], v[70:71], v[76:77]
	v_cndmask_b32_e64 v75, v75, v67, s[80:81]
	v_cndmask_b32_e64 v74, v74, v66, s[80:81]
	v_pk_add_f32 v[66:67], v[126:127], v[70:71]
	v_pk_add_f32 v[68:69], v[72:73], v[68:69]
	ds_read_b128 v[70:73], v135 offset:4096
	v_cndmask_b32_e64 v77, v77, v129, s[80:81]
	v_cndmask_b32_e64 v76, v76, v128, s[80:81]
	v_mul_f32_e32 v16, 0x3fb8aa3b, v68
	v_mul_f32_e32 v119, 0x3fb8aa3b, v66
	s_waitcnt lgkmcnt(0)
; __device__ __forceinline__ unsigned cvt_pk_bf16(float lo, float hi) { unsigned r; asm("v_cvt_pk_bf16_f32 %0, %1, %2" : "=v"(r) : "v"(lo), "v"(hi)); return r; }
; __device__ __forceinline__ void hg_block(ArgsP a_, int jl, unsigned char* smem) { const ArgsP a = a_;
;     ...
;           for (int k = 0; k < 16; ++k) { const f32x4 t = *(const f32x4*)(TOT + k * 128 + c4); if (k < rg) pre = pre + t; if (k < 8) gmid = gmid + t; glast = glast + t; }
;           f32x4 Emid, Elm;
; #pragma unroll
;           for (int e = 0; e < 4; ++e) { Emid[e] = __expf(gmid[e]); Elm[e] = __expf(glast[e] - gmid[e]); }
;           float ktv[4][4];
; #pragma unroll
;           for (int r = 0; r < 4; ++r) { const int i = 4 * rg + r; const f32x4 d = pre + cs[r] - gmid;
;               const f32x4 q = {__uint_as_float(q2[r].x << 16), __uint_as_float(q2[r].x & 0xffff0000u), __uint_as_float(q2[r].y << 16), __uint_as_float(q2[r].y & 0xffff0000u)};
;               const f32x4 kk = {__uint_as_float(kk2[r].x << 16), __uint_as_float(kk2[r].x & 0xffff0000u), __uint_as_float(kk2[r].y << 16), __uint_as_float(kk2[r].y & 0xffff0000u)};
;               f32x4 qa, qs, kb;
; #pragma unroll
;               for (int e = 0; e < 4; ++e) { const float eq = __expf(d[e]), ek = __expf(-d[e]); qa[e] = q[e] * eq; qs[e] = qa[e] * Emid[e]; kb[e] = kk[e] * ek; ktv[r][e] = kb[e] * Elm[e]; }
;               *(u32x2*)(QA + i * LQ + c4) = (u32x2){cvt_pk_bf16(qa[0], qa[1]), cvt_pk_bf16(qa[2], qa[3])};
;               *(u32x2*)(QS + i * LQ + c4) = (u32x2){cvt_pk_bf16(qs[0], qs[1]), cvt_pk_bf16(qs[2], qs[3])};
;               *(u32x2*)(KB + i * LQ + c4) = (u32x2){cvt_pk_bf16(kb[0], kb[1]), cvt_pk_bf16(kb[2], kb[3])}; }
	v_pk_add_f32 v[126:127], v[70:71], v[74:75]
	v_pk_add_f32 v[128:129], v[72:73], v[76:77]
	v_cndmask_b32_e64 v75, v75, v127, s[82:83]
	v_cndmask_b32_e64 v74, v74, v126, s[82:83]
	v_cndmask_b32_e64 v77, v77, v129, s[82:83]
	v_cndmask_b32_e64 v76, v76, v128, s[82:83]
	v_pk_add_f32 v[126:127], v[66:67], v[72:73]
	v_pk_add_f32 v[128:129], v[68:69], v[70:71]
	ds_read_b128 v[70:73], v135 offset:4608
	v_exp_f32_e32 v16, v16
	v_exp_f32_e32 v119, v119
	s_waitcnt lgkmcnt(0)
	v_pk_add_f32 v[130:131], v[70:71], v[74:75]
	v_pk_add_f32 v[132:133], v[72:73], v[76:77]
	v_pk_add_f32 v[126:127], v[126:127], v[72:73]
	v_pk_add_f32 v[128:129], v[128:129], v[70:71]
	ds_read_b128 v[70:73], v135 offset:5120
	v_cndmask_b32_e64 v75, v75, v131, s[84:85]
	v_cndmask_b32_e64 v74, v74, v130, s[84:85]
	v_cndmask_b32_e64 v77, v77, v133, s[84:85]
	v_cndmask_b32_e64 v76, v76, v132, s[84:85]
	s_waitcnt lgkmcnt(0)
	v_pk_add_f32 v[130:131], v[70:71], v[74:75]
	v_pk_add_f32 v[132:133], v[72:73], v[76:77]
	v_pk_add_f32 v[126:127], v[126:127], v[72:73]
	v_pk_add_f32 v[128:129], v[128:129], v[70:71]
	ds_read_b128 v[70:73], v135 offset:5632
	v_cndmask_b32_e64 v75, v75, v131, s[86:87]
	v_cndmask_b32_e64 v74, v74, v130, s[86:87]
	v_cndmask_b32_e64 v77, v77, v133, s[86:87]
	v_cndmask_b32_e64 v76, v76, v132, s[86:87]
	s_waitcnt lgkmcnt(0)
	v_pk_add_f32 v[130:131], v[70:71], v[74:75]
	v_pk_add_f32 v[132:133], v[72:73], v[76:77]
	v_pk_add_f32 v[126:127], v[126:127], v[72:73]
	v_pk_add_f32 v[128:129], v[128:129], v[70:71]
	ds_read_b128 v[70:73], v135 offset:6144
	v_cndmask_b32_e64 v75, v75, v131, s[88:89]
	v_cndmask_b32_e64 v74, v74, v130, s[88:89]
	v_cndmask_b32_e64 v77, v77, v133, s[88:89]
	v_cndmask_b32_e64 v76, v76, v132, s[88:89]
	s_waitcnt lgkmcnt(0)
	v_pk_add_f32 v[130:131], v[70:71], v[74:75]
	v_pk_add_f32 v[132:133], v[72:73], v[76:77]
	v_pk_add_f32 v[126:127], v[126:127], v[72:73]
	v_pk_add_f32 v[128:129], v[128:129], v[70:71]
	ds_read_b128 v[70:73], v135 offset:6656
	v_cndmask_b32_e64 v75, v75, v131, s[90:91]
	v_cndmask_b32_e64 v74, v74, v130, s[90:91]
	v_cndmask_b32_e64 v77, v77, v133, s[90:91]
	v_cndmask_b32_e64 v76, v76, v132, s[90:91]
	s_waitcnt lgkmcnt(0)
	v_pk_add_f32 v[130:131], v[70:71], v[74:75]
	v_pk_add_f32 v[132:133], v[72:73], v[76:77]
	v_pk_add_f32 v[126:127], v[126:127], v[72:73]
	v_pk_add_f32 v[128:129], v[128:129], v[70:71]
	ds_read_b128 v[70:73], v135 offset:7168
	v_cndmask_b32_e64 v75, v75, v131, s[92:93]
	v_cndmask_b32_e64 v74, v74, v130, s[92:93]
	v_cndmask_b32_e64 v77, v77, v133, s[92:93]
	v_cndmask_b32_e64 v76, v76, v132, s[92:93]
	s_waitcnt lgkmcnt(0)
	v_pk_add_f32 v[130:131], v[70:71], v[74:75]
	v_pk_add_f32 v[132:133], v[72:73], v[76:77]
	v_cndmask_b32_e64 v131, v75, v131, s[94:95]
	v_cndmask_b32_e64 v130, v74, v130, s[94:95]
	v_pk_add_f32 v[126:127], v[126:127], v[72:73]
	ds_read_b128 v[72:75], v135 offset:7680
	v_cndmask_b32_e64 v77, v77, v133, s[94:95]
	v_cndmask_b32_e64 v76, v76, v132, s[94:95]
	v_pk_add_f32 v[128:129], v[128:129], v[70:71]
	s_waitcnt lgkmcnt(0)
	v_pk_add_f32 v[132:133], v[72:73], v[130:131]
	v_pk_add_f32 v[72:73], v[128:129], v[72:73]
	v_cndmask_b32_e64 v129, v130, v132, s[96:97]
	v_add_f32_e32 v64, v64, v129
	v_sub_f32_e32 v64, v64, v68
	v_mul_f32_e32 v179, 0x3fb8aa3b, v64
	v_mul_f32_e32 v64, 0xbfb8aa3b, v64
	v_exp_f32_e32 v64, v64
	v_cndmask_b32_e64 v128, v131, v133, s[96:97]
	v_pk_add_f32 v[176:177], v[74:75], v[76:77]
	v_pk_add_f32 v[70:71], v[126:127], v[74:75]
	v_mul_f32_e32 v175, v64, v175
	v_add_f32_e32 v64, v65, v128
	v_sub_f32_e32 v64, v64, v69
	v_mul_f32_e32 v65, 0x3fb8aa3b, v64
	v_mul_f32_e32 v64, 0xbfb8aa3b, v64
	v_exp_f32_e32 v64, v64
	v_cndmask_b32_e64 v76, v76, v176, s[96:97]
	v_add_f32_e32 v62, v62, v76
	v_and_b32_e32 v176, 0xffff0000, v78
	v_sub_f32_e32 v62, v62, v66
	v_mul_f32_e32 v176, v64, v176
	v_mul_f32_e32 v64, 0x3fb8aa3b, v62
	v_mul_f32_e32 v62, 0xbfb8aa3b, v62
	v_exp_f32_e32 v62, v62
	v_cndmask_b32_e64 v77, v77, v177, s[96:97]
	v_lshlrev_b32_e32 v177, 16, v79
	v_sub_f32_e32 v74, v72, v68
	v_mul_f32_e32 v177, v62, v177
	v_add_f32_e32 v62, v63, v77
	v_sub_f32_e32 v62, v62, v67
	v_mul_f32_e32 v63, 0x3fb8aa3b, v62
	v_mul_f32_e32 v75, 0x3fb8aa3b, v69
	v_mul_f32_e32 v126, 0x3fb8aa3b, v67
	v_exp_f32_e32 v179, v179
	v_exp_f32_e32 v65, v65
	v_exp_f32_e32 v64, v64
	v_exp_f32_e32 v63, v63
	v_mul_f32_e32 v74, 0x3fb8aa3b, v74
	v_exp_f32_e32 v75, v75
	v_exp_f32_e32 v126, v126
	v_mul_f32_e32 v62, 0xbfb8aa3b, v62
	v_exp_f32_e32 v74, v74
	v_exp_f32_e32 v62, v62
	v_lshlrev_b32_e32 v130, 16, v80
	v_and_b32_e32 v131, 0xffff0000, v80
	v_lshlrev_b32_e32 v132, 16, v81
	v_and_b32_e32 v133, 0xffff0000, v81
	v_mul_f32_e32 v130, v179, v130
	v_mul_f32_e32 v65, v65, v131
	v_mul_f32_e32 v64, v64, v132
	v_mul_f32_e32 v63, v63, v133
	v_add_f32_e32 v60, v60, v129
	v_mul_f32_e32 v179, v16, v130
	v_mul_f32_e32 v131, v75, v65
	v_mul_f32_e32 v132, v119, v64
	v_mul_f32_e32 v133, v126, v63
	v_cvt_pk_bf16_f32 v63, v64, v63
	v_cvt_pk_bf16_f32 v64, v179, v131
	v_sub_f32_e32 v60, v60, v68
	v_mul_f32_e32 v180, v74, v175
	v_mul_f32_e32 v178, v62, v178
	v_cvt_pk_bf16_f32 v62, v130, v65
	v_cvt_pk_bf16_f32 v65, v132, v133
	ds_write_b64 v106, v[64:65] offset:34816
	v_cvt_pk_bf16_f32 v64, v175, v176
	v_mul_f32_e32 v175, 0x3fb8aa3b, v60
	v_mul_f32_e32 v60, 0xbfb8aa3b, v60
	v_exp_f32_e32 v60, v60
	v_lshlrev_b32_e32 v130, 16, v86
	v_add_f32_e32 v58, v58, v76
	v_and_b32_e32 v131, 0xffff0000, v86
	v_mul_f32_e32 v130, v60, v130
	v_add_f32_e32 v60, v61, v128
	v_sub_f32_e32 v60, v60, v69
	v_mul_f32_e32 v61, 0x3fb8aa3b, v60
	v_mul_f32_e32 v60, 0xbfb8aa3b, v60
	v_exp_f32_e32 v60, v60
	v_sub_f32_e32 v58, v58, v66
	v_lshlrev_b32_e32 v132, 16, v87
; __device__ __forceinline__ unsigned cvt_pk_bf16(float lo, float hi) { unsigned r; asm("v_cvt_pk_bf16_f32 %0, %1, %2" : "=v"(r) : "v"(lo), "v"(hi)); return r; }
; __device__ __forceinline__ void hg_block(ArgsP a_, int jl, unsigned char* smem) { const ArgsP a = a_;
;     ...
;           for (int r = 0; r < 4; ++r) { const int i = 4 * rg + r; const f32x4 d = pre + cs[r] - gmid;
;               const f32x4 q = {__uint_as_float(q2[r].x << 16), __uint_as_float(q2[r].x & 0xffff0000u), __uint_as_float(q2[r].y << 16), __uint_as_float(q2[r].y & 0xffff0000u)};
;               const f32x4 kk = {__uint_as_float(kk2[r].x << 16), __uint_as_float(kk2[r].x & 0xffff0000u), __uint_as_float(kk2[r].y << 16), __uint_as_float(kk2[r].y & 0xffff0000u)};
;               f32x4 qa, qs, kb;
; #pragma unroll
;               for (int e = 0; e < 4; ++e) { const float eq = __expf(d[e]), ek = __expf(-d[e]); qa[e] = q[e] * eq; qs[e] = qa[e] * Emid[e]; kb[e] = kk[e] * ek; ktv[r][e] = kb[e] * Elm[e]; }
;               *(u32x2*)(QA + i * LQ + c4) = (u32x2){cvt_pk_bf16(qa[0], qa[1]), cvt_pk_bf16(qa[2], qa[3])};
;               *(u32x2*)(QS + i * LQ + c4) = (u32x2){cvt_pk_bf16(qs[0], qs[1]), cvt_pk_bf16(qs[2], qs[3])};
;               *(u32x2*)(KB + i * LQ + c4) = (u32x2){cvt_pk_bf16(kb[0], kb[1]), cvt_pk_bf16(kb[2], kb[3])}; }
; #pragma unroll
;           for (int e = 0; e < 4; ++e) {
;               *(u32x2*)(KT + (c4 + e) * LJ + 4 * rg) = (u32x2){cvt_pk_bf16(ktv[0][e], ktv[1][e]), cvt_pk_bf16(ktv[2][e], ktv[3][e])};
;               unsigned vv[4];
; #pragma unroll
;               for (int r = 0; r < 4; ++r) { const unsigned w = (e < 2) ? v2[r].x : v2[r].y; vv[r] = (e & 1) ? (w >> 16) : (w & 0xffffu); }
;               *(u32x2*)(VT + (c4 + e) * LJ + 4 * rg) = (u32x2){vv[0] | (vv[1] << 16), vv[2] | (vv[3] << 16)}; }
;           if (rg == 0) { f32x4 sd;
; #pragma unroll
;               for (int e = 0; e < 4; ++e) sd[e] = __expf(glast[e]);
;               *(f32x4*)(SDEC + c4) = sd; } }
	v_sub_f32_e32 v117, v73, v69
	v_mul_f32_e32 v131, v60, v131
	v_mul_f32_e32 v60, 0x3fb8aa3b, v58
	v_mul_f32_e32 v58, 0xbfb8aa3b, v58
	v_exp_f32_e32 v58, v58
	v_exp_f32_e32 v175, v175
	v_exp_f32_e32 v61, v61
	v_exp_f32_e32 v60, v60
	v_mul_f32_e32 v132, v58, v132
	v_add_f32_e32 v58, v59, v77
	v_sub_f32_e32 v58, v58, v67
	v_mul_f32_e32 v59, 0x3fb8aa3b, v58
	v_exp_f32_e32 v59, v59
	v_mul_f32_e32 v117, 0x3fb8aa3b, v117
	v_mul_f32_e32 v58, 0xbfb8aa3b, v58
	v_exp_f32_e32 v117, v117
	v_cvt_pk_bf16_f32 v65, v177, v178
	v_exp_f32_e32 v58, v58
	ds_write2st64_b64 v106, v[62:63], v[64:65] offset1:34
	v_lshlrev_b32_e32 v62, 16, v88
	v_and_b32_e32 v63, 0xffff0000, v88
	v_lshlrev_b32_e32 v64, 16, v89
	v_and_b32_e32 v65, 0xffff0000, v89
	v_mul_f32_e32 v62, v175, v62
	v_mul_f32_e32 v61, v61, v63
	v_mul_f32_e32 v60, v60, v64
	v_mul_f32_e32 v59, v59, v65
	v_add_f32_e32 v56, v56, v129
	v_and_b32_e32 v133, 0xffff0000, v87
	v_mul_f32_e32 v175, v16, v62
	v_mul_f32_e32 v63, v75, v61
	v_mul_f32_e32 v64, v119, v60
	v_mul_f32_e32 v65, v126, v59
	v_cvt_pk_bf16_f32 v59, v60, v59
	v_cvt_pk_bf16_f32 v60, v175, v63
	v_sub_f32_e32 v56, v56, v68
	v_mul_f32_e32 v181, v117, v176
	v_mul_f32_e32 v176, v74, v130
	v_mul_f32_e32 v133, v58, v133
	v_cvt_pk_bf16_f32 v58, v62, v61
	v_cvt_pk_bf16_f32 v61, v64, v65
	ds_write_b64 v108, v[60:61] offset:34816
	v_cvt_pk_bf16_f32 v60, v130, v131
	v_mul_f32_e32 v130, 0x3fb8aa3b, v56
	v_mul_f32_e32 v56, 0xbfb8aa3b, v56
	v_exp_f32_e32 v56, v56
	v_lshlrev_b32_e32 v62, 16, v98
	v_add_f32_e32 v54, v54, v76
	v_and_b32_e32 v63, 0xffff0000, v98
	v_mul_f32_e32 v62, v56, v62
	v_add_f32_e32 v56, v57, v128
	v_sub_f32_e32 v56, v56, v69
	v_mul_f32_e32 v57, 0x3fb8aa3b, v56
	v_mul_f32_e32 v56, 0xbfb8aa3b, v56
	v_exp_f32_e32 v56, v56
	v_sub_f32_e32 v54, v54, v66
	v_lshlrev_b32_e32 v64, 16, v99
	v_sub_f32_e32 v123, v70, v66
	v_mul_f32_e32 v63, v56, v63
	v_mul_f32_e32 v56, 0x3fb8aa3b, v54
	v_mul_f32_e32 v54, 0xbfb8aa3b, v54
	v_exp_f32_e32 v54, v54
	v_exp_f32_e32 v130, v130
	v_exp_f32_e32 v57, v57
	v_exp_f32_e32 v56, v56
	v_mul_f32_e32 v64, v54, v64
	v_add_f32_e32 v54, v55, v77
	v_sub_f32_e32 v54, v54, v67
	v_mul_f32_e32 v55, 0x3fb8aa3b, v54
	v_exp_f32_e32 v55, v55
	v_mul_f32_e32 v123, 0x3fb8aa3b, v123
	v_mul_f32_e32 v54, 0xbfb8aa3b, v54
	v_exp_f32_e32 v123, v123
	v_cvt_pk_bf16_f32 v61, v132, v133
	v_exp_f32_e32 v54, v54
	ds_write2st64_b64 v108, v[58:59], v[60:61] offset1:34
	v_lshlrev_b32_e32 v58, 16, v100
	v_and_b32_e32 v59, 0xffff0000, v100
	v_lshlrev_b32_e32 v60, 16, v101
	v_and_b32_e32 v61, 0xffff0000, v101
	v_mul_f32_e32 v58, v130, v58
	v_mul_f32_e32 v57, v57, v59
	v_mul_f32_e32 v56, v56, v60
	v_mul_f32_e32 v55, v55, v61
	v_add_f32_e32 v50, v50, v129
	v_and_b32_e32 v65, 0xffff0000, v99
	v_mul_f32_e32 v130, v16, v58
	v_mul_f32_e32 v59, v75, v57
	v_mul_f32_e32 v60, v119, v56
	v_mul_f32_e32 v61, v126, v55
	v_cvt_pk_bf16_f32 v55, v56, v55
	v_cvt_pk_bf16_f32 v56, v130, v59
	v_sub_f32_e32 v50, v50, v68
	v_mul_f32_e32 v182, v123, v177
	v_mul_f32_e32 v177, v117, v131
	v_mul_f32_e32 v131, v74, v62
	v_mul_f32_e32 v65, v54, v65
	v_cvt_pk_bf16_f32 v54, v58, v57
	v_cvt_pk_bf16_f32 v57, v60, v61
	ds_write_b64 v147, v[56:57] offset:34816
	v_cvt_pk_bf16_f32 v56, v62, v63
	v_mul_f32_e32 v62, 0x3fb8aa3b, v50
	v_mul_f32_e32 v50, 0xbfb8aa3b, v50
	v_exp_f32_e32 v50, v50
	v_lshlrev_b32_e32 v58, 16, v110
	v_and_b32_e32 v59, 0xffff0000, v110
	v_lshlrev_b32_e32 v60, 16, v111
	v_mul_f32_e32 v58, v50, v58
	v_add_f32_e32 v50, v51, v128
	v_sub_f32_e32 v50, v50, v69
	v_mul_f32_e32 v51, 0x3fb8aa3b, v50
	v_mul_f32_e32 v50, 0xbfb8aa3b, v50
	v_exp_f32_e32 v50, v50
	v_exp_f32_e32 v62, v62
	v_exp_f32_e32 v51, v51
	v_sub_f32_e32 v127, v71, v67
	v_mul_f32_e32 v59, v50, v59
	v_add_f32_e32 v50, v52, v76
	v_sub_f32_e32 v50, v50, v66
	v_mul_f32_e32 v52, 0x3fb8aa3b, v50
	v_mul_f32_e32 v50, 0xbfb8aa3b, v50
	v_exp_f32_e32 v50, v50
	v_exp_f32_e32 v52, v52
	v_mul_f32_e32 v127, 0x3fb8aa3b, v127
	v_cvt_pk_bf16_f32 v57, v64, v65
	v_mul_f32_e32 v60, v50, v60
	v_add_f32_e32 v50, v53, v77
	v_sub_f32_e32 v50, v50, v67
	v_mul_f32_e32 v53, 0x3fb8aa3b, v50
	v_mul_f32_e32 v50, 0xbfb8aa3b, v50
	v_exp_f32_e32 v53, v53
	v_exp_f32_e32 v50, v50
	ds_write2st64_b64 v147, v[54:55], v[56:57] offset1:34
	v_lshlrev_b32_e32 v54, 16, v112
	v_and_b32_e32 v55, 0xffff0000, v112
	v_lshlrev_b32_e32 v56, 16, v113
	v_exp_f32_e32 v127, v127
	v_and_b32_e32 v57, 0xffff0000, v113
	v_and_b32_e32 v61, 0xffff0000, v111
	v_mul_f32_e32 v54, v62, v54
	v_mul_f32_e32 v51, v51, v55
	v_mul_f32_e32 v52, v52, v56
	v_mul_f32_e32 v16, v16, v54
	v_mul_f32_e32 v55, v75, v51
	v_mul_f32_e32 v56, v119, v52
	v_mul_f32_e32 v53, v53, v57
	v_mul_f32_e32 v61, v50, v61
	v_cvt_pk_bf16_f32 v50, v54, v51
	v_cvt_pk_bf16_f32 v51, v52, v53
	v_cvt_pk_bf16_f32 v52, v16, v55
	v_mul_f32_e32 v57, v126, v53
	v_cvt_pk_bf16_f32 v53, v56, v57
	ds_write_b64 v165, v[52:53] offset:34816
	v_cvt_pk_bf16_f32 v52, v58, v59
	v_and_b32_e32 v16, 0xffff, v82
	v_mul_f32_e32 v62, v74, v58
	v_cvt_pk_bf16_f32 v53, v60, v61
	ds_write2st64_b64 v165, v[50:51], v[52:53] offset1:34
	v_cvt_pk_bf16_f32 v50, v180, v176
	v_cvt_pk_bf16_f32 v51, v131, v62
	v_lshl_or_b32 v52, v90, 16, v16
	v_add_u32_e32 v16, 0xc800, v166
	v_mul_f32_e32 v183, v127, v178
	v_mul_f32_e32 v178, v123, v132
	v_mul_f32_e32 v132, v117, v63
	v_mul_f32_e32 v63, v117, v59
	v_and_b32_e32 v53, 0xffff, v102
	v_cvt_pk_bf16_f32 v54, v181, v177
	v_cvt_pk_bf16_f32 v55, v132, v63
	ds_write2_b64 v16, v[50:51], v[54:55] offset0:128 offset1:146
	v_lshrrev_b32_e32 v50, 16, v82
	v_lshrrev_b32_e32 v51, 16, v102
	v_lshl_or_b32 v53, v120, 16, v53
	v_and_or_b32 v50, v90, s49, v50
	v_and_or_b32 v51, v120, s49, v51
	v_mul_f32_e32 v179, v127, v133
	v_mul_f32_e32 v133, v123, v64
	v_mul_f32_e32 v64, v123, v60
	ds_write2_b64 v167, v[52:53], v[50:51] offset1:18
	v_cvt_pk_bf16_f32 v51, v133, v64
	v_mul_f32_e32 v175, v127, v65
	v_mul_f32_e32 v65, v127, v61
	v_cvt_pk_bf16_f32 v50, v182, v178
	v_and_b32_e32 v52, 0xffff, v83
	v_and_b32_e32 v53, 0xffff, v103
	v_cvt_pk_bf16_f32 v54, v183, v179
	v_cvt_pk_bf16_f32 v55, v175, v65
	ds_write2_b64 v16, v[50:51], v[54:55] offset0:164 offset1:182
	v_lshrrev_b32_e32 v16, 16, v83
	v_lshrrev_b32_e32 v51, 16, v103
	v_lshl_or_b32 v52, v91, 16, v52
	v_lshl_or_b32 v53, v121, 16, v53
	v_and_or_b32 v50, v91, s49, v16
	v_and_or_b32 v51, v121, s49, v51
	ds_write2_b64 v167, v[52:53], v[50:51] offset0:36 offset1:54
	s_mov_b64 s[52:53], exec
	v_readlane_b32 s54, v255, 12
	v_readlane_b32 s55, v255, 13
	s_and_b64 s[54:55], s[52:53], s[54:55]
	s_mov_b64 exec, s[54:55]
	s_cbranch_execz .LBB0_414
	v_mul_f32_e32 v16, 0x3fb8aa3b, v72
	v_exp_f32_e32 v50, v16
	v_mul_f32_e32 v16, 0x3fb8aa3b, v73
	v_exp_f32_e32 v51, v16
	v_mul_f32_e32 v16, 0x3fb8aa3b, v70
	v_exp_f32_e32 v52, v16
	v_mul_f32_e32 v16, 0x3fb8aa3b, v71
	v_exp_f32_e32 v53, v16
	ds_write_b128 v137, v[50:53]

; __device__ __forceinline__ unsigned cvt_pk_bf16(float lo, float hi) { unsigned r; asm("v_cvt_pk_bf16_f32 %0, %1, %2" : "=v"(r) : "v"(lo), "v"(hi)); return r; }
; template <int DK, int DV, bool SEPQ> ...
;     ...
;         for (int vt = 0; vt < NVT; ++vt) { const f32x4 s = S[ct][vt]; u32x2 w; w.x = cvt_pk_bf16(s[0], s[1]); w.y = cvt_pk_bf16(s[2], s[3]);
;             *(u32x2*)(ST + (16 * vt + fr) * LQ + 16 * (wid * NCTW + ct) + 4 * fq) = w; }
;     __syncthreads();
;     {
;         const float gi_i = GI[16 * m + fr];
;         const int n0 = 2 * hw, n1 = 2 * hw + 1; const bool do0 = n0 <= m, do1 = n1 <= m;
;         f32x4 acc0 = {0.f, 0.f, 0.f, 0.f}, acc1 = {0.f, 0.f, 0.f, 0.f};
; #pragma unroll
;         for (int vt = 0; vt < NVTW; ++vt) O[vt] = (f32x4){0.f, 0.f, 0.f, 0.f};
; #pragma unroll
;         for (int ks = 0; ks < DK / 32; ++ks) {
;             const bf16x8 qf = *(const bf16x8*)(QA + (16 * m + fr) * LQ + 32 * ks + 8 * fq);
;             if (do0) { const bf16x8 kf = *(const bf16x8*)(KB + (16 * n0 + fr) * LQ + 32 * ks + 8 * fq); acc0 = __builtin_amdgcn_mfma_f32_16x16x32_bf16(kf, qf, acc0, 0, 0, 0); }
; __device__ __forceinline__ void hg_block(ArgsP a_, int jl, unsigned char* smem) { const ArgsP a = a_;
;     ...
;         if (uu + 1 < ntot_) HG_LOAD(un_);
;     ...
;                 const f32x4 gg = *(const f32x4*)(ng + h * 128 + v); const u32x2 gt = gcur[vt];
.LBB0_419:
	s_lshl_b32 s52, s52, 7
	s_and_b32 s52, s52, 0x380
	v_or_b32_e32 v16, s52, v93
	v_mov_b32_e32 v117, v17
	v_mov_b32_e32 v119, v17
	v_add_u32_e32 v202, s54, v136
	v_ashrrev_i32_e32 v203, 31, v202
	v_lshlrev_b64 v[202:203], 10, v[202:203]
	v_or_b32_e32 v202, v202, v16
	v_lshl_add_u64 v[204:205], v[202:203], 2, s[34:35]
	global_load_dwordx4 v[0:3], v[204:205], off
	v_lshlrev_b64 v[202:203], 1, v[202:203]
	v_lshl_add_u64 v[204:205], s[18:19], 0, v[202:203]
	global_load_dwordx2 v[82:83], v[204:205], off
	v_lshl_add_u64 v[204:205], s[22:23], 0, v[202:203]
	global_load_dwordx2 v[78:79], v[204:205], off
	v_lshl_add_u64 v[204:205], s[26:27], 0, v[202:203]
	global_load_dwordx2 v[80:81], v[204:205], off
	v_add_u32_e32 v202, s54, v107
	v_ashrrev_i32_e32 v203, 31, v202
	v_lshlrev_b64 v[202:203], 10, v[202:203]
	v_or_b32_e32 v202, v202, v16
	v_lshl_add_u64 v[204:205], v[202:203], 2, s[34:35]
	global_load_dwordx4 v[4:7], v[204:205], off
	v_lshlrev_b64 v[202:203], 1, v[202:203]
	v_lshl_add_u64 v[204:205], s[18:19], 0, v[202:203]
	global_load_dwordx2 v[90:91], v[204:205], off
	v_lshl_add_u64 v[204:205], s[22:23], 0, v[202:203]
	global_load_dwordx2 v[86:87], v[204:205], off
	v_lshl_add_u64 v[204:205], s[26:27], 0, v[202:203]
	global_load_dwordx2 v[88:89], v[204:205], off
	v_add_u32_e32 v202, s54, v109
	v_ashrrev_i32_e32 v203, 31, v202
	v_lshlrev_b64 v[202:203], 10, v[202:203]
	v_or_b32_e32 v202, v202, v16
	v_lshl_add_u64 v[204:205], v[202:203], 2, s[34:35]
	global_load_dwordx4 v[8:11], v[204:205], off
	v_lshlrev_b64 v[202:203], 1, v[202:203]
	v_lshl_add_u64 v[204:205], s[18:19], 0, v[202:203]
	global_load_dwordx2 v[102:103], v[204:205], off
	v_lshl_add_u64 v[204:205], s[22:23], 0, v[202:203]
	global_load_dwordx2 v[98:99], v[204:205], off
	v_lshl_add_u64 v[204:205], s[26:27], 0, v[202:203]
	global_load_dwordx2 v[100:101], v[204:205], off
	v_add_u32_e32 v202, s54, v164
	v_ashrrev_i32_e32 v203, 31, v202
	v_lshlrev_b64 v[202:203], 10, v[202:203]
	v_or_b32_e32 v202, v202, v16
	v_lshl_add_u64 v[204:205], v[202:203], 2, s[34:35]
	global_load_dwordx4 v[12:15], v[204:205], off
	v_lshlrev_b64 v[202:203], 1, v[202:203]
	v_lshl_add_u64 v[204:205], s[18:19], 0, v[202:203]
	global_load_dwordx2 v[120:121], v[204:205], off
	v_lshl_add_u64 v[204:205], s[22:23], 0, v[202:203]
	global_load_dwordx2 v[110:111], v[204:205], off
	v_lshl_add_u64 v[204:205], s[26:27], 0, v[202:203]
	global_load_dwordx2 v[112:113], v[204:205], off
	s_lshl_b32 s52, s52, 1
	s_mov_b32 s53, s12
	v_add_u32_e32 v50, s54, v134
	v_ashrrev_i32_e32 v51, 31, v50
	v_readlane_b32 s54, v255, 6
	v_lshlrev_b64 v[50:51], 11, v[50:51]
	v_readlane_b32 s55, v255, 7
	s_nop 1
	v_lshl_add_u64 v[50:51], s[54:55], 0, v[50:51]
	v_lshl_add_u64 v[50:51], v[50:51], 0, s[52:53]
	v_lshl_add_u64 v[50:51], v[50:51], 0, v[116:117]
	v_lshl_add_u64 v[50:51], v[50:51], 0, v[118:119]
	global_load_dwordx2 v[132:133], v[50:51], off
	global_load_dwordx2 v[130:131], v[50:51], off offset:32
	global_load_dwordx2 v[128:129], v[50:51], off offset:64
	global_load_dwordx2 v[126:127], v[50:51], off offset:96
.LBB0_420:
	s_lshl_b32 s54, s62, 9
	s_mov_b32 s55, s12
	v_lshl_add_u64 v[218:219], v[114:115], 0, s[54:55]
	global_load_dwordx4 v[202:205], v[218:219], off
	global_load_dwordx4 v[206:209], v[218:219], off offset:64
	global_load_dwordx4 v[210:213], v[218:219], off offset:128
	global_load_dwordx4 v[214:217], v[218:219], off offset:192
	v_cvt_pk_bf16_f32 v50, v18, v19
	v_cvt_pk_bf16_f32 v51, v20, v21
	ds_write_b64 v169, v[50:51]
	v_cvt_pk_bf16_f32 v50, v22, v23
	v_cvt_pk_bf16_f32 v51, v24, v25
	ds_write_b64 v169, v[50:51] offset:4352
	v_cvt_pk_bf16_f32 v50, v26, v27
	v_cvt_pk_bf16_f32 v51, v28, v29
	ds_write_b64 v169, v[50:51] offset:8704
	v_cvt_pk_bf16_f32 v50, v30, v31
	v_cvt_pk_bf16_f32 v51, v32, v33
	ds_write_b64 v169, v[50:51] offset:13056
	v_cvt_pk_bf16_f32 v50, v34, v35
	v_cvt_pk_bf16_f32 v51, v36, v37
	ds_write_b64 v169, v[50:51] offset:17408
	v_cvt_pk_bf16_f32 v50, v38, v39
	v_cvt_pk_bf16_f32 v51, v40, v41
	ds_write_b64 v169, v[50:51] offset:21760
	v_cvt_pk_bf16_f32 v50, v42, v43
	v_cvt_pk_bf16_f32 v51, v44, v45
	ds_write_b64 v169, v[50:51] offset:26112
	v_cvt_pk_bf16_f32 v50, v46, v47
	v_cvt_pk_bf16_f32 v51, v48, v49
	ds_write_b64 v169, v[50:51] offset:30464
	s_waitcnt lgkmcnt(0)
	s_barrier
	ds_read_b32 v16, v138
	ds_read_b128 v[58:61], v139
	v_mov_b32_e32 v52, v17
	v_mov_b32_e32 v53, v17
	v_mov_b32_e32 v50, 0
	v_mov_b32_e32 v51, v17
	v_mov_b64_e32 v[56:57], v[52:53]
	v_mov_b64_e32 v[54:55], v[50:51]
	s_and_saveexec_b64 s[52:53], s[44:45]
	s_cbranch_execz .LBB0_422
	ds_read_b128 v[54:57], v140 offset:17408
	s_waitcnt lgkmcnt(0)
	v_mfma_f32_16x16x32_bf16 v[54:57], v[54:57], v[58:61], 0

; __device__ __forceinline__ unsigned cvt_pk_bf16(float lo, float hi) { unsigned r; asm("v_cvt_pk_bf16_f32 %0, %1, %2" : "=v"(r) : "v"(lo), "v"(hi)); return r; }
; __device__ __forceinline__ void hg_block(ArgsP a_, int jl, unsigned char* smem) { const ArgsP a = a_;
;     ...
;         __syncthreads();
;         if (irow < len) { const float rstd = rsqrtf((RSm[irow * 2] + RSm[irow * 2 + 1]) * (1.f / 128.f) + LN_EPS);
; #pragma unroll
;             for (int vt = 0; vt < 4; ++vt) { const int v = 16 * (hw * 4 + vt) + 4 * fq; const size_t o = (size_t)(row0 + irow) * 1024 + h * 128 + v;
;                 const f32x4 gg = *(const f32x4*)(ng + h * 128 + v); const u32x2 gt = gcur[vt];
;                 const float g0 = __uint_as_float(gt.x << 16), g1 = __uint_as_float(gt.x & 0xffff0000u), g2 = __uint_as_float(gt.y << 16), g3 = __uint_as_float(gt.y & 0xffff0000u);
;                 u32x2 w; w.x = cvt_pk_bf16(O[vt][0] * rstd * gg[0] * g0, O[vt][1] * rstd * gg[1] * g1); w.y = cvt_pk_bf16(O[vt][2] * rstd * gg[2] * g2, O[vt][3] * rstd * gg[3] * g3);
;                 *(u32x2*)(ON + o) = w; } }
.LBB0_438:
	s_or_b64 exec, exec, s[52:53]
	v_cmp_gt_i32_e32 vcc, s64, v134
	s_waitcnt lgkmcnt(0)
	s_barrier
	s_and_saveexec_b64 s[52:53], vcc
	s_cbranch_execz .LBB0_440
	v_add_u32_e32 v16, 0, v145
	v_add_u32_e32 v16, 0x22b00, v16
	ds_read_b64 v[66:67], v16
	s_lshl_b32 s54, s62, 8
	v_readlane_b32 s55, v255, 8
	s_add_u32 s54, s55, s54
	v_readlane_b32 s55, v255, 9
	s_waitcnt lgkmcnt(0)
	v_add_f32_e32 v16, v66, v67
	v_fmamk_f32 v16, v16, 0x3c000000, v187
	v_cmp_gt_f32_e32 vcc, s31, v16
	v_mul_f32_e32 v66, 0x4b800000, v16
	s_addc_u32 s55, s55, 0
	v_cndmask_b32_e32 v16, v16, v66, vcc
	v_rsq_f32_e32 v16, v16
	v_lshlrev_b32_e32 v74, 16, v124
	v_and_b32_e32 v75, 0xffff0000, v124
	v_lshlrev_b32_e32 v76, 16, v125
	v_mul_f32_e32 v66, 0x45800000, v16
	v_cndmask_b32_e32 v16, v16, v66, vcc
	v_add_u32_e32 v66, s63, v134
	v_ashrrev_i32_e32 v67, 31, v66
	v_lshlrev_b64 v[66:67], 11, v[66:67]
	v_lshl_add_u64 v[72:73], s[54:55], 0, v[66:67]
	s_lshl_b32 s54, s62, 9
	s_mov_b32 s55, s12
	v_lshl_add_u64 v[66:67], v[114:115], 0, s[54:55]
	v_mul_f32_e32 v62, v62, v16
	v_mul_f32_e32 v63, v63, v16
	v_and_b32_e32 v77, 0xffff0000, v125
	v_mov_b32_e32 v123, v17
	v_mul_f32_e32 v58, v58, v16
	v_mul_f32_e32 v59, v59, v16
	v_mul_f32_e32 v54, v54, v16
	v_mul_f32_e32 v55, v55, v16
	v_mul_f32_e32 v50, v50, v16
	v_mul_f32_e32 v51, v51, v16
	s_waitcnt vmcnt(0)
	v_mul_f32_e32 v62, v202, v62
	v_mul_f32_e32 v63, v203, v63
	v_mul_f32_e32 v62, v62, v74
	v_mul_f32_e32 v63, v63, v75
	v_cvt_pk_bf16_f32 v68, v62, v63
	v_mul_f32_e32 v62, v64, v16
	v_mul_f32_e32 v63, v65, v16
	v_mul_f32_e32 v62, v204, v62
	v_mul_f32_e32 v63, v205, v63
	v_mul_f32_e32 v62, v62, v76
	v_mul_f32_e32 v63, v63, v77
	v_cvt_pk_bf16_f32 v69, v62, v63
	v_lshl_add_u64 v[62:63], v[72:73], 0, v[122:123]
	global_store_dwordx2 v[62:63], v[68:69], off
	v_lshlrev_b32_e32 v64, 16, v104
	v_and_b32_e32 v65, 0xffff0000, v104
	v_lshlrev_b32_e32 v72, 16, v105
	v_and_b32_e32 v73, 0xffff0000, v105
	v_mul_f32_e32 v58, v206, v58
	v_mul_f32_e32 v59, v207, v59
	v_mul_f32_e32 v58, v58, v64
	v_mul_f32_e32 v59, v59, v65
	v_cvt_pk_bf16_f32 v58, v58, v59
	v_mul_f32_e32 v59, v60, v16
	v_mul_f32_e32 v59, v208, v59
	v_mul_f32_e32 v60, v61, v16
	v_mul_f32_e32 v59, v59, v72
	v_mul_f32_e32 v60, v209, v60
	v_mul_f32_e32 v60, v60, v73
	v_cvt_pk_bf16_f32 v59, v59, v60
	global_store_dwordx2 v[62:63], v[58:59], off offset:32
	v_lshlrev_b32_e32 v64, 16, v94
	v_and_b32_e32 v65, 0xffff0000, v94
	v_lshlrev_b32_e32 v68, 16, v95
	v_and_b32_e32 v69, 0xffff0000, v95
	v_mul_f32_e32 v54, v54, v210
	v_mul_f32_e32 v55, v55, v211
	v_mul_f32_e32 v54, v54, v64
	v_mul_f32_e32 v55, v55, v65
	v_cvt_pk_bf16_f32 v54, v54, v55
	v_mul_f32_e32 v55, v56, v16
	v_mul_f32_e32 v55, v55, v212
	v_mul_f32_e32 v56, v57, v16
	v_mul_f32_e32 v55, v55, v68
	v_mul_f32_e32 v56, v56, v213
	v_mul_f32_e32 v56, v56, v69
	v_cvt_pk_bf16_f32 v55, v55, v56
	global_store_dwordx2 v[62:63], v[54:55], off offset:64
	v_lshlrev_b32_e32 v58, 16, v84
	v_and_b32_e32 v59, 0xffff0000, v84
	v_lshlrev_b32_e32 v60, 16, v85
	v_and_b32_e32 v61, 0xffff0000, v85
	v_mul_f32_e32 v50, v50, v214
	v_mul_f32_e32 v51, v51, v215
	v_mul_f32_e32 v50, v50, v58
	v_mul_f32_e32 v51, v51, v59
	v_cvt_pk_bf16_f32 v50, v50, v51
	v_mul_f32_e32 v51, v52, v16
	v_mul_f32_e32 v51, v51, v216
	v_mul_f32_e32 v16, v53, v16
	v_mul_f32_e32 v51, v51, v60
	v_mul_f32_e32 v16, v16, v217
	v_mul_f32_e32 v16, v16, v61
	v_cvt_pk_bf16_f32 v51, v51, v16
	global_store_dwordx2 v[62:63], v[50:51], off offset:96
